# D-phase SSM scan: u words derived from the loaded A fragments via ds_bpermute instead of 8 duplicate global loads per item (same bytes); vmcnt immediates recomputed
# speedup vs baseline: 1.0392x; 1.0072x over previous
.LBB0_742:
	v_and_b32_e32 v206, 3, v194
	v_lshlrev_b32_e32 v206, 2, v206
	v_and_b32_e32 v207, 12, v194
	v_lshl_or_b32 v206, v207, 3, v206
	v_and_b32_e32 v207, 32, v194
	v_lshl_or_b32 v206, v207, 2, v206
	v_add_u32_e32 v207, 16, v206
	v_and_b32_e32 v208, 16, v194
	s_ashr_i32 s22, s48, 6
	s_cmpk_lt_i32 s22, 0x80
	s_cselect_b64 s[44:45], -1, 0
	s_cmpk_gt_i32 s22, 0x7f
	s_cselect_b64 s[42:43], -1, 0
	v_mov_b32_e32 v6, v194
	s_mov_b64 s[0:1], -1
	s_and_b64 vcc, exec, s[42:43]
	s_cbranch_vccz .LBB0_744
	s_and_b32 s0, s48, 0xffffffc0
	s_add_i32 s23, s0, 0x2000
	s_add_i32 s24, s0, 0x2020
	s_mov_b64 s[0:1], 0

.LBB0_754:
	v_and_b32_e32 v0, 3, v6
	v_lshrrev_b32_e32 v1, 1, v6
	v_and_or_b32 v0, v1, 12, v0
	v_and_b32_e32 v1, 4, v6
	v_mov_b32_e32 v2, s24
	v_mov_b32_e32 v3, s23
	v_cmp_eq_u32_e32 vcc, 0, v1
	s_lshl_b32 s22, s25, 4
	v_and_b32_e32 v160, 15, v6
	v_cndmask_b32_e32 v1, v2, v3, vcc
	v_add_u32_e32 v2, v0, v1
	v_mov_b64_e32 v[0:1], s[86:87]
	v_mad_i64_i32 v[0:1], s[0:1], v2, s66, v[0:1]
	v_or_b32_e32 v2, s22, v160
	v_lshlrev_b32_e32 v2, 8, v2
	v_mov_b32_e32 v3, v173
	v_lshl_add_u64 v[2:3], s[34:35], 0, v[2:3]
	v_and_b32_e32 v34, 48, v6
	v_mov_b32_e32 v35, v173
	v_lshl_add_u64 v[2:3], v[2:3], 0, v[34:35]
	global_load_dword v157, v[4:5], off
	global_load_dwordx4 v[80:83], v[2:3], off
	global_load_dwordx4 v[76:79], v[2:3], off offset:64
	global_load_dwordx4 v[72:75], v[2:3], off offset:128
	global_load_dwordx4 v[68:71], v[2:3], off offset:192
	v_lshrrev_b32_e32 v2, 2, v6
	v_and_b32_e32 v4, 12, v2
	v_or_b32_e32 v2, s20, v4
	v_readlane_b32 s4, v237, 4
	v_or_b32_e32 v2, s22, v2
	v_mov_b32_e32 v3, v173
	v_readlane_b32 s10, v237, 10
	v_readlane_b32 s11, v237, 11
	v_lshlrev_b32_e32 v7, 3, v36
	s_lshl_b32 s94, s25, 5
	v_lshl_add_u64 v[2:3], v[2:3], 2, s[10:11]
	v_lshl_add_u64 v[0:1], v[0:1], 0, s[94:95]
	global_load_dwordx4 v[64:67], v[2:3], off
	v_lshlrev_b32_e32 v2, 1, v7
	v_mov_b32_e32 v3, v173
	s_add_u32 s0, s86, s94
	v_lshl_add_u64 v[2:3], v[0:1], 0, v[2:3]
	s_addc_u32 s1, s87, 0
	v_lshlrev_b32_e32 v120, 1, v4
	v_mov_b32_e32 v121, v173
	v_lshl_add_u64 v[0:1], s[0:1], 0, v[120:121]
	v_add_co_u32_e32 v4, vcc, s92, v2
	v_add_u32_e32 v16, s23, v160
	s_nop 0
	v_addc_co_u32_e32 v5, vcc, 0, v3, vcc
	v_mad_i64_i32 v[6:7], s[0:1], v16, s66, v[0:1]
	v_add_co_u32_e32 v8, vcc, s92, v6
	v_add_u32_e32 v17, s24, v160
	s_nop 0
	v_addc_co_u32_e32 v9, vcc, 0, v7, vcc
	global_load_dwordx4 v[48:51], v[4:5], off
	global_load_dwordx2 v[152:153], v[6:7], off offset:2048
	v_mad_i64_i32 v[4:5], s[0:1], v17, s66, v[0:1]
	v_add_co_u32_e32 v6, vcc, s92, v4
	s_mov_b32 s0, 0x32000
	s_nop 0
	v_addc_co_u32_e32 v7, vcc, 0, v5, vcc
	v_or_b32_e32 v10, 16, v160
	global_load_dwordx2 v[112:113], v[4:5], off offset:2048
	v_add_co_u32_e32 v4, vcc, s0, v2
	v_add_u32_e32 v18, s23, v10
	s_nop 0
	v_addc_co_u32_e32 v5, vcc, 0, v3, vcc
	v_mad_i64_i32 v[6:7], s[0:1], v18, s66, v[0:1]
	v_add_co_u32_e32 v8, vcc, s92, v6
	v_add_u32_e32 v33, s24, v10
	s_nop 0
	v_addc_co_u32_e32 v9, vcc, 0, v7, vcc
	global_load_dwordx4 v[108:111], v[4:5], off
	global_load_dwordx2 v[144:145], v[6:7], off offset:2048
	v_mad_i64_i32 v[4:5], s[0:1], v33, s66, v[0:1]
	v_add_co_u32_e32 v6, vcc, 0x2000, v4
	s_mov_b64 s[0:1], 0x2000
	s_nop 0
	v_addc_co_u32_e32 v7, vcc, 0, v5, vcc
	global_load_dwordx2 v[140:141], v[4:5], off offset:2048
	v_cndmask_b32_e64 v4, 0, 1, s[44:45]
	v_lshl_add_u64 v[2:3], v[2:3], 0, s[0:1]
	v_cmp_ne_u32_e64 s[0:1], 1, v4
	v_or_b32_e32 v4, 32, v160
	s_andn2_b64 vcc, exec, s[44:45]
	v_add_u32_e32 v165, s23, v4
	v_add_u32_e32 v164, s24, v4
	v_readlane_b32 s5, v237, 5
	v_readlane_b32 s6, v237, 6
	v_readlane_b32 s7, v237, 7
	v_readlane_b32 s8, v237, 8
	v_readlane_b32 s9, v237, 9
	v_readlane_b32 s12, v237, 12
	v_readlane_b32 s13, v237, 13
	v_readlane_b32 s14, v237, 14
	v_readlane_b32 s15, v237, 15
	v_readlane_b32 s16, v237, 16
	v_readlane_b32 s17, v237, 17
	v_readlane_b32 s18, v237, 18
	v_readlane_b32 s19, v237, 19
	s_cbranch_vccnz .LBB0_756
	v_add_co_u32_e32 v4, vcc, 0x60000, v2
	v_mad_i64_i32 v[6:7], s[26:27], v165, s66, v[0:1]
	s_nop 0
	v_addc_co_u32_e32 v5, vcc, 0, v3, vcc
	v_add_co_u32_e32 v8, vcc, 0x2000, v6
	global_load_dwordx4 v[104:107], v[4:5], off
	global_load_dwordx2 v[136:137], v[6:7], off offset:2048
	v_addc_co_u32_e32 v9, vcc, 0, v7, vcc
	v_mad_i64_i32 v[4:5], s[26:27], v164, s66, v[0:1]
	v_add_co_u32_e32 v6, vcc, 0x2000, v4
	s_nop 1
	v_addc_co_u32_e32 v7, vcc, 0, v5, vcc
	global_load_dwordx2 v[132:133], v[4:5], off offset:2048
.LBB0_756:
	v_or_b32_e32 v4, 48, v160
	s_and_b64 vcc, exec, s[0:1]
	v_add_u32_e32 v162, s23, v4
	v_add_u32_e32 v117, s24, v4
	s_cbranch_vccnz .LBB0_758
	v_add_co_u32_e32 v2, vcc, 0x90000, v2
	v_mad_i64_i32 v[4:5], s[24:25], v162, s66, v[0:1]
	s_nop 0
	v_addc_co_u32_e32 v3, vcc, 0, v3, vcc
	v_add_co_u32_e32 v6, vcc, 0x2000, v4
	v_mad_i64_i32 v[0:1], s[24:25], v117, s66, v[0:1]
	s_nop 0
	v_addc_co_u32_e32 v7, vcc, 0, v5, vcc
	global_load_dwordx4 v[100:103], v[2:3], off
	global_load_dwordx2 v[126:127], v[4:5], off offset:2048
	v_add_co_u32_e32 v2, vcc, 0x2000, v0
	s_nop 1
	v_addc_co_u32_e32 v3, vcc, 0, v1, vcc
	global_load_dwordx2 v[118:119], v[0:1], off offset:2048
.LBB0_758:
	s_waitcnt vmcnt(11)
	ds_bpermute_b32 v202, v206, v48
	ds_bpermute_b32 v203, v206, v49
	ds_bpermute_b32 v204, v206, v50
	ds_bpermute_b32 v205, v206, v51
	ds_bpermute_b32 v210, v207, v48
	ds_bpermute_b32 v211, v207, v49
	ds_bpermute_b32 v212, v207, v50
	ds_bpermute_b32 v213, v207, v51
	v_mfma_f32_32x32x16_bf16 v[0:15], v[48:51], v[84:87], 0
	v_mad_i64_i32 v[176:177], s[24:25], v16, s66, 0
	v_mad_i64_i32 v[178:179], s[24:25], v17, s66, 0
	v_mad_i64_i32 v[150:151], s[24:25], v18, s66, 0
	v_mov_b32_e32 v131, v53
	v_mfma_f32_32x32x16_bf16 v[16:31], v[48:51], v[88:91], 0
	v_lshlrev_b32_e32 v53, 2, v32
	v_mul_u32_u24_e32 v54, 0x1200, v36
	v_mov_b32_e32 v130, v125
	v_add3_u32 v163, s53, v53, v54
	v_mov_b32_e32 v125, v52
	s_nop 1
	v_mov_b32_e32 v52, v0
	v_mad_i64_i32 v[148:149], s[24:25], v33, s66, 0
	s_nop 2
	v_mov_b32_e32 v53, v16
	v_pk_fma_f32 v[52:53], v[124:125], v[114:115], v[52:53]
	v_add_u32_e32 v166, s53, v34
	v_mfma_f32_32x32x16_bf16 v[32:47], v[48:51], v[92:95], 0
	v_fma_f32 v174, -v130, v156, v52
	v_fma_f32 v175, -v131, v157, v53
	v_mov_b32_e32 v16, v1
	s_lshl_b32 s94, s22, 1
	v_mov_b32_e32 v121, v173
	s_movk_i32 s4, 0x120
	v_mul_u32_u24_e32 v167, 0x120, v160
	s_nop 4
	v_mov_b32_e32 v180, v32
	v_mfma_f32_32x32x16_bf16 v[48:63], v[48:51], v[96:99], 0
	s_waitcnt lgkmcnt(0)
	v_cmp_ne_u32_e64 s[26:27], 0, v208
	v_cndmask_b32_e64 v158, v202, v204, s[26:27]
	v_cndmask_b32_e64 v159, v203, v205, s[26:27]
	v_cndmask_b32_e64 v154, v210, v212, s[26:27]
	v_cndmask_b32_e64 v155, v211, v213, s[26:27]
	s_nop 11
	v_mov_b32_e32 v181, v48
	v_pk_fma_f32 v[156:157], v[124:125], v[156:157], v[180:181]
	v_mov_b32_e32 v48, v33
	v_pk_fma_f32 v[114:115], v[130:131], v[114:115], v[156:157]
	v_mov_b32_e32 v33, v18
	v_cvt_pk_bf16_f32 v0, v174, v114
	ds_write_b32 v163, v0
	v_cvt_pk_bf16_f32 v0, v175, v115
	ds_write_b32 v163, v0 offset:128
	v_pk_fma_f32 v[0:1], v[124:125], v[174:175], v[16:17]
	v_pk_fma_f32 v[16:17], v[124:125], v[114:115], v[48:49]
	v_pk_fma_f32 v[0:1], v[130:131], v[114:115], v[0:1] neg_lo:[1,0,0] neg_hi:[1,0,0]
	v_pk_fma_f32 v[16:17], v[130:131], v[174:175], v[16:17]
	v_mov_b32_e32 v48, v34
	v_cvt_pk_bf16_f32 v32, v0, v16
	ds_write_b32 v163, v32 offset:288
	v_cvt_pk_bf16_f32 v32, v1, v17
	ds_write_b32 v163, v32 offset:416
	v_mov_b32_e32 v32, v2
	v_pk_fma_f32 v[32:33], v[124:125], v[0:1], v[32:33]
	v_mov_b32_e32 v49, v50
	v_pk_fma_f32 v[32:33], v[130:131], v[16:17], v[32:33] neg_lo:[1,0,0] neg_hi:[1,0,0]
	v_pk_fma_f32 v[16:17], v[124:125], v[16:17], v[48:49]
	v_mov_b32_e32 v18, v3
	v_pk_fma_f32 v[0:1], v[130:131], v[0:1], v[16:17]
	v_mov_b32_e32 v50, v35
	v_cvt_pk_bf16_f32 v2, v32, v0
	ds_write_b32 v163, v2 offset:576
	v_cvt_pk_bf16_f32 v2, v33, v1
	ds_write_b32 v163, v2 offset:704
	v_pk_fma_f32 v[2:3], v[124:125], v[32:33], v[18:19]
	v_mov_b32_e32 v17, v20
	v_pk_fma_f32 v[2:3], v[130:131], v[0:1], v[2:3] neg_lo:[1,0,0] neg_hi:[1,0,0]
	v_pk_fma_f32 v[0:1], v[124:125], v[0:1], v[50:51]
	v_mov_b32_e32 v18, v36
	v_pk_fma_f32 v[0:1], v[130:131], v[32:33], v[0:1]
	v_mov_b32_e32 v19, v52
	v_cvt_pk_bf16_f32 v16, v2, v0
	ds_write_b32 v163, v16 offset:864
	v_cvt_pk_bf16_f32 v16, v3, v1
	ds_write_b32 v163, v16 offset:992
	v_mov_b32_e32 v16, v4
	v_pk_fma_f32 v[16:17], v[124:125], v[2:3], v[16:17]
	v_mov_b32_e32 v20, v5
	v_pk_fma_f32 v[16:17], v[130:131], v[0:1], v[16:17] neg_lo:[1,0,0] neg_hi:[1,0,0]
	v_pk_fma_f32 v[0:1], v[124:125], v[0:1], v[18:19]
	v_mov_b32_e32 v52, v37
	v_pk_fma_f32 v[0:1], v[130:131], v[2:3], v[0:1]
	v_mov_b32_e32 v5, v22
	v_cvt_pk_bf16_f32 v2, v16, v0
	ds_write_b32 v163, v2 offset:1152
	v_cvt_pk_bf16_f32 v2, v17, v1
	ds_write_b32 v163, v2 offset:1280
	v_pk_fma_f32 v[2:3], v[124:125], v[16:17], v[20:21]
	v_mov_b32_e32 v22, v7
	v_pk_fma_f32 v[2:3], v[130:131], v[0:1], v[2:3] neg_lo:[1,0,0] neg_hi:[1,0,0]
	v_pk_fma_f32 v[0:1], v[124:125], v[0:1], v[52:53]
	s_waitcnt vmcnt(10)
	v_lshlrev_b32_e32 v20, 16, v152
	v_pk_fma_f32 v[0:1], v[130:131], v[16:17], v[0:1]
	v_and_b32_e32 v18, 0xffff0000, v152
	v_cvt_pk_bf16_f32 v4, v2, v0
	ds_write_b32 v163, v4 offset:1440
	v_cvt_pk_bf16_f32 v4, v3, v1
	ds_write_b32 v163, v4 offset:1568
	v_mov_b32_e32 v4, v6
	v_pk_fma_f32 v[4:5], v[124:125], v[2:3], v[4:5]
	v_lshl_add_u64 v[48:49], s[86:87], 0, v[178:179]
	v_pk_fma_f32 v[34:35], v[130:131], v[0:1], v[4:5] neg_lo:[1,0,0] neg_hi:[1,0,0]
	v_mov_b32_e32 v4, v38
	v_mov_b32_e32 v5, v54
	v_pk_fma_f32 v[0:1], v[124:125], v[0:1], v[4:5]
	v_mul_f32_e32 v4, 0xbfb8aa3b, v18
	v_pk_fma_f32 v[0:1], v[130:131], v[2:3], v[0:1]
	v_exp_f32_e32 v4, v4
	v_cvt_pk_bf16_f32 v2, v34, v0
	ds_write_b32 v163, v2 offset:1728
	v_cvt_pk_bf16_f32 v2, v35, v1
	ds_write_b32 v163, v2 offset:1856
	v_pk_fma_f32 v[2:3], v[124:125], v[34:35], v[22:23]
	v_add_f32_e32 v6, 1.0, v4
	v_pk_fma_f32 v[36:37], v[130:131], v[0:1], v[2:3] neg_lo:[1,0,0] neg_hi:[1,0,0]
	v_mul_f32_e32 v2, 0xbfb8aa3b, v20
	v_exp_f32_e32 v2, v2
	v_lshlrev_b32_e32 v4, 16, v153
	v_lshl_add_u64 v[48:49], v[48:49], 0, s[94:95]
	v_rcp_f32_e32 v32, v6
	v_add_f32_e32 v2, 1.0, v2
	v_rcp_f32_e32 v22, v2
	v_mul_f32_e32 v2, 0xbfb8aa3b, v4
	v_exp_f32_e32 v16, v2
	v_and_b32_e32 v2, 0xffff0000, v153
	v_mul_f32_e32 v17, 0xbfb8aa3b, v2
	v_exp_f32_e32 v17, v17
	v_add_f32_e32 v6, 1.0, v16
	v_lshl_add_u64 v[152:153], v[48:49], 0, v[120:121]
	s_waitcnt vmcnt(9)
	v_lshlrev_b32_e32 v48, 16, v112
	v_rcp_f32_e32 v16, v6
	v_add_f32_e32 v6, 1.0, v17
	v_mul_f32_e32 v17, 0xbfb8aa3b, v48
	v_and_b32_e32 v50, 0xffff0000, v112
	v_exp_f32_e32 v17, v17
	v_mul_f32_e32 v21, 0xbfb8aa3b, v50
	v_exp_f32_e32 v21, v21
	v_mov_b32_e32 v54, v39
	v_pk_fma_f32 v[38:39], v[124:125], v[0:1], v[54:55]
	v_add_f32_e32 v17, 1.0, v17
	v_pk_fma_f32 v[34:35], v[130:131], v[34:35], v[38:39]
	v_mov_b32_e32 v38, v8
	v_mov_b32_e32 v39, v24
	v_rcp_f32_e32 v52, v17
	v_add_f32_e32 v17, 1.0, v21
	v_cvt_pk_bf16_f32 v21, v36, v34
	v_pk_fma_f32 v[38:39], v[124:125], v[36:37], v[38:39]
	v_mov_b32_e32 v54, v40
	v_mov_b32_e32 v55, v56
	ds_write_b32 v163, v21 offset:2016
	v_cvt_pk_bf16_f32 v21, v37, v35
	v_pk_fma_f32 v[38:39], v[130:131], v[34:35], v[38:39] neg_lo:[1,0,0] neg_hi:[1,0,0]
	v_pk_fma_f32 v[34:35], v[124:125], v[34:35], v[54:55]
	v_mov_b32_e32 v24, v9
	v_pk_fma_f32 v[34:35], v[130:131], v[36:37], v[34:35]
	v_mov_b32_e32 v56, v41
	v_cvt_pk_bf16_f32 v8, v38, v34
	ds_write_b32 v163, v8 offset:2304
	v_cvt_pk_bf16_f32 v8, v39, v35
	ds_write_b32 v163, v8 offset:2432
	v_pk_fma_f32 v[8:9], v[124:125], v[38:39], v[24:25]
	v_pk_fma_f32 v[24:25], v[124:125], v[34:35], v[56:57]
	v_pk_fma_f32 v[8:9], v[130:131], v[34:35], v[8:9] neg_lo:[1,0,0] neg_hi:[1,0,0]
	v_mov_b32_e32 v34, v10
	v_mov_b32_e32 v35, v26
	ds_write_b32 v163, v21 offset:2144
	v_pk_fma_f32 v[24:25], v[130:131], v[38:39], v[24:25]
	v_pk_fma_f32 v[34:35], v[124:125], v[8:9], v[34:35]
	v_cvt_pk_bf16_f32 v21, v8, v24
	v_mov_b32_e32 v36, v42
	v_mov_b32_e32 v37, v58
	ds_write_b32 v163, v21 offset:2592
	v_cvt_pk_bf16_f32 v21, v9, v25
	v_pk_fma_f32 v[34:35], v[130:131], v[24:25], v[34:35] neg_lo:[1,0,0] neg_hi:[1,0,0]
	v_pk_fma_f32 v[24:25], v[124:125], v[24:25], v[36:37]
	v_mov_b32_e32 v26, v11
	v_pk_fma_f32 v[8:9], v[130:131], v[8:9], v[24:25]
	v_mov_b32_e32 v58, v43
	v_cvt_pk_bf16_f32 v10, v34, v8
	ds_write_b32 v163, v10 offset:2880
	v_cvt_pk_bf16_f32 v10, v35, v9
	ds_write_b32 v163, v10 offset:3008
	v_pk_fma_f32 v[10:11], v[124:125], v[34:35], v[26:27]
	v_mov_b32_e32 v24, v12
	v_pk_fma_f32 v[10:11], v[130:131], v[8:9], v[10:11] neg_lo:[1,0,0] neg_hi:[1,0,0]
	v_pk_fma_f32 v[8:9], v[124:125], v[8:9], v[58:59]
	v_mov_b32_e32 v25, v28
	ds_write_b32 v163, v21 offset:2720
	v_pk_fma_f32 v[8:9], v[130:131], v[34:35], v[8:9]
	v_pk_fma_f32 v[24:25], v[124:125], v[10:11], v[24:25]
	v_cvt_pk_bf16_f32 v21, v10, v8
	v_mov_b32_e32 v26, v44
	v_mov_b32_e32 v27, v60
	ds_write_b32 v163, v21 offset:3168
	v_cvt_pk_bf16_f32 v21, v11, v9
	v_pk_fma_f32 v[24:25], v[130:131], v[8:9], v[24:25] neg_lo:[1,0,0] neg_hi:[1,0,0]
	v_pk_fma_f32 v[8:9], v[124:125], v[8:9], v[26:27]
	v_mov_b32_e32 v28, v13
	v_pk_fma_f32 v[8:9], v[130:131], v[10:11], v[8:9]
	v_mov_b32_e32 v60, v45
	v_cvt_pk_bf16_f32 v10, v24, v8
	ds_write_b32 v163, v10 offset:3456
	v_cvt_pk_bf16_f32 v10, v25, v9
	ds_write_b32 v163, v10 offset:3584
	v_pk_fma_f32 v[10:11], v[124:125], v[24:25], v[28:29]
	v_mov_b32_e32 v13, v30
	v_pk_fma_f32 v[10:11], v[130:131], v[8:9], v[10:11] neg_lo:[1,0,0] neg_hi:[1,0,0]
	v_pk_fma_f32 v[8:9], v[124:125], v[8:9], v[60:61]
	v_mov_b32_e32 v30, v15
	v_pk_fma_f32 v[8:9], v[130:131], v[24:25], v[8:9]
	v_mov_b32_e32 v24, v46
	v_cvt_pk_bf16_f32 v12, v10, v8
	ds_write_b32 v163, v12 offset:3744
	v_cvt_pk_bf16_f32 v12, v11, v9
	ds_write_b32 v163, v12 offset:3872
	v_mov_b32_e32 v12, v14
	v_pk_fma_f32 v[12:13], v[124:125], v[10:11], v[12:13]
	v_mov_b32_e32 v25, v62
	v_pk_fma_f32 v[12:13], v[130:131], v[8:9], v[12:13] neg_lo:[1,0,0] neg_hi:[1,0,0]
	v_pk_fma_f32 v[8:9], v[124:125], v[8:9], v[24:25]
	v_mov_b32_e32 v62, v47
	v_pk_fma_f32 v[8:9], v[130:131], v[10:11], v[8:9]
	v_mad_u32_u24 v174, v160, s4, v166
	v_cvt_pk_bf16_f32 v10, v12, v8
	ds_write_b32 v163, v10 offset:4032
	v_cvt_pk_bf16_f32 v10, v13, v9
	ds_write_b32 v163, v10 offset:4160
	v_pk_fma_f32 v[10:11], v[124:125], v[12:13], v[30:31]
	v_lshl_add_u64 v[0:1], s[86:87], 0, v[176:177]
	v_pk_fma_f32 v[160:161], v[130:131], v[8:9], v[10:11] neg_lo:[1,0,0] neg_hi:[1,0,0]
	v_pk_fma_f32 v[8:9], v[124:125], v[8:9], v[62:63]
	ds_write_b32 v163, v21 offset:3296
	v_pk_fma_f32 v[176:177], v[130:131], v[12:13], v[8:9]
	v_lshlrev_b32_e32 v49, 16, v154
	v_cvt_pk_bf16_f32 v8, v160, v176
	ds_write_b32 v163, v8 offset:4320
	v_cvt_pk_bf16_f32 v8, v161, v177
	ds_write_b32 v163, v8 offset:4448
	ds_read_b128 v[8:11], v174
	ds_read_b128 v[12:15], v174 offset:64
	s_waitcnt lgkmcnt(1)
	v_mfma_f32_16x16x32_bf16 v[8:11], v[80:83], v[8:11], 0
	ds_read_b128 v[24:27], v174 offset:128
	v_and_b32_e32 v51, 0xffff0000, v154
	v_and_b32_e32 v154, 0xffff0000, v113
	s_waitcnt lgkmcnt(1)
	v_mfma_f32_16x16x32_bf16 v[8:11], v[76:79], v[12:15], v[8:11]
	v_mul_f32_e32 v12, 0xbfb8aa3b, v154
	v_exp_f32_e32 v21, v12
	ds_read_b128 v[12:15], v174 offset:192
	s_waitcnt lgkmcnt(1)
	v_mfma_f32_16x16x32_bf16 v[8:11], v[72:75], v[24:27], v[8:11]
	v_lshlrev_b32_e32 v3, 16, v158
	v_and_b32_e32 v5, 0xffff0000, v158
	v_lshlrev_b32_e32 v56, 16, v113
	s_waitcnt lgkmcnt(0)
	v_mfma_f32_16x16x32_bf16 v[8:11], v[68:71], v[12:15], v[8:11]
	v_rcp_f32_e32 v54, v17
	v_mul_f32_e32 v17, 0xbfb8aa3b, v56
	v_exp_f32_e32 v17, v17
	v_lshlrev_b32_e32 v7, 16, v159
	v_and_b32_e32 v19, 0xffff0000, v159
	s_nop 2
	v_fma_f32 v23, v64, v3, v8
	v_mul_f32_e32 v3, 0x3d372713, v23
	v_fma_f32 v33, v65, v5, v9
	v_mul_f32_e32 v3, v23, v3
	v_mul_f32_e32 v5, 0x3d372713, v33
	v_fma_f32 v3, v23, v3, v23
	v_mul_f32_e32 v5, v33, v5
	v_mul_f32_e32 v3, 0x3fcc422a, v3
	v_fma_f32 v5, v33, v5, v33
	v_mul_f32_e32 v3, 0xbfb8aa3b, v3
	v_mul_f32_e32 v5, 0x3fcc422a, v5
	v_exp_f32_e32 v3, v3
	v_mul_f32_e32 v5, 0xbfb8aa3b, v5
	v_exp_f32_e32 v5, v5
	v_add_f32_e32 v17, 1.0, v17
	v_rcp_f32_e32 v58, v17
	v_add_f32_e32 v17, 1.0, v21
	v_rcp_f32_e32 v156, v17
	v_add_f32_e32 v3, 1.0, v3
	v_fma_f32 v17, v66, v7, v10
	v_rcp_f32_e32 v21, v3
	v_add_f32_e32 v3, 1.0, v5
	v_mul_f32_e32 v5, 0x3d372713, v17
	v_mul_f32_e32 v5, v17, v5
	v_fma_f32 v5, v17, v5, v17
	v_mul_f32_e32 v5, 0x3fcc422a, v5
	v_fmac_f32_e32 v11, v67, v19
	v_mul_f32_e32 v5, 0xbfb8aa3b, v5
	v_mul_f32_e32 v7, 0x3d372713, v11
	v_exp_f32_e32 v5, v5
	v_mul_f32_e32 v7, v11, v7
	v_fma_f32 v7, v11, v7, v11
	v_mul_f32_e32 v7, 0x3fcc422a, v7
	v_mul_f32_e32 v7, 0xbfb8aa3b, v7
	v_exp_f32_e32 v7, v7
	v_rcp_f32_e32 v19, v3
	v_add_f32_e32 v3, 1.0, v5
	v_rcp_f32_e32 v5, v3
	ds_read_b128 v[12:15], v174 offset:4608
	v_add_f32_e32 v3, 1.0, v7
	v_pk_mul_f32 v[18:19], v[32:33], v[18:19]
	v_rcp_f32_e32 v6, v6
	v_rcp_f32_e32 v3, v3
	v_pk_mul_f32 v[8:9], v[22:23], v[20:21]
	v_mul_f32_e32 v23, v18, v19
	v_cvt_pk_bf16_f32 v10, v9, v19
	v_pk_mul_f32 v[4:5], v[16:17], v[4:5]
	ds_read_b128 v[16:19], v174 offset:4672
	s_waitcnt lgkmcnt(1)
	v_mfma_f32_16x16x32_bf16 v[12:15], v[80:83], v[12:15], 0
	v_mov_b32_e32 v7, v11
	v_lshl_add_u64 v[0:1], v[0:1], 0, s[94:95]
	v_mul_f32_e32 v22, v8, v9
	v_pk_mul_f32 v[20:21], v[6:7], v[2:3]
	ds_read_b128 v[6:9], v174 offset:4736
	v_lshl_add_u64 v[0:1], v[0:1], 0, v[120:121]
	v_mul_f32_e32 v24, v4, v5
	v_cvt_pk_bf16_f32 v11, v5, v21
	s_waitcnt lgkmcnt(1)
	v_mfma_f32_16x16x32_bf16 v[2:5], v[76:79], v[16:19], v[12:15]
	v_lshlrev_b32_e32 v157, 16, v155
	v_and_b32_e32 v155, 0xffff0000, v155
	s_nop 0
	v_add_co_u32_e32 v12, vcc, s92, v0
	s_nop 1
	v_addc_co_u32_e32 v13, vcc, 0, v1, vcc
	global_store_dwordx2 v[12:13], v[10:11], off
	ds_read_b128 v[10:13], v174 offset:4800
	s_waitcnt lgkmcnt(1)
	v_mfma_f32_16x16x32_bf16 v[2:5], v[72:75], v[6:9], v[2:5]
	v_mul_f32_e32 v7, v20, v21
	v_cvt_pk_bf16_f32 v6, v22, v23
	v_cvt_pk_bf16_f32 v7, v24, v7
	s_waitcnt lgkmcnt(0)
	v_mfma_f32_16x16x32_bf16 v[112:115], v[68:71], v[10:13], v[2:5]
	global_store_dwordx2 v[0:1], v[6:7], off offset:2048
	s_nop 6
	v_fma_f32 v53, v64, v49, v112
	v_mul_f32_e32 v2, 0x3d372713, v53
	v_mul_f32_e32 v2, v53, v2
	v_fma_f32 v2, v53, v2, v53
	v_mul_f32_e32 v2, 0x3fcc422a, v2
	v_mul_f32_e32 v2, 0xbfb8aa3b, v2
	v_exp_f32_e32 v2, v2
	v_fma_f32 v55, v65, v51, v113
	v_fma_f32 v59, v66, v157, v114
	v_mul_f32_e32 v3, 0x3d372713, v55
	v_add_f32_e32 v0, 1.0, v2
	v_rcp_f32_e32 v49, v0
	v_mul_f32_e32 v0, 0x3d372713, v59
	v_mul_f32_e32 v3, v55, v3
	v_mul_f32_e32 v0, v59, v0
	v_fma_f32 v3, v55, v3, v55
	v_fma_f32 v0, v59, v0, v59
	v_mul_f32_e32 v3, 0x3fcc422a, v3
	v_mul_f32_e32 v16, 0x3fcc422a, v0
	v_mul_f32_e32 v3, 0xbfb8aa3b, v3
	v_mul_f32_e32 v16, 0xbfb8aa3b, v16
	v_fmac_f32_e32 v115, v67, v155
	v_exp_f32_e32 v3, v3
	v_exp_f32_e32 v33, v16
	v_mul_f32_e32 v16, 0x3d372713, v115
	v_mul_f32_e32 v16, v115, v16
	v_fma_f32 v16, v115, v16, v115
	v_mul_f32_e32 v34, 0x3fcc422a, v16
	v_add_f32_e32 v32, 1.0, v3
	v_mul_f32_e32 v34, 0xbfb8aa3b, v34
	v_exp_f32_e32 v34, v34
	v_rcp_f32_e32 v51, v32
	v_add_f32_e32 v32, 1.0, v33
	v_rcp_f32_e32 v57, v32
	v_add_f32_e32 v32, 1.0, v34
	v_pk_mul_f32 v[48:49], v[52:53], v[48:49]
	v_pk_mul_f32 v[50:51], v[54:55], v[50:51]
	s_waitcnt vmcnt(10)
	ds_bpermute_b32 v202, v206, v108
	ds_bpermute_b32 v203, v206, v109
	ds_bpermute_b32 v204, v206, v110
	ds_bpermute_b32 v205, v206, v111
	ds_bpermute_b32 v210, v207, v108
	ds_bpermute_b32 v211, v207, v109
	ds_bpermute_b32 v212, v207, v110
	ds_bpermute_b32 v213, v207, v111
	v_mfma_f32_32x32x16_bf16 v[0:15], v[108:111], v[84:87], 0
	v_rcp_f32_e32 v155, v32
	v_mul_f32_e32 v114, v48, v49
	v_cvt_pk_bf16_f32 v112, v49, v51
	v_mul_f32_e32 v175, v50, v51
	v_pk_mul_f32 v[158:159], v[58:59], v[56:57]
	v_mov_b32_e32 v157, v115
	v_mul_f32_e32 v158, v158, v159
	v_mfma_f32_32x32x16_bf16 v[16:31], v[108:111], v[88:91], 0
	v_add_u32_e32 v115, 0xc00, v163
	v_mfma_f32_32x32x16_bf16 v[32:47], v[108:111], v[92:95], 0
	v_mfma_f32_32x32x16_bf16 v[48:63], v[108:111], v[96:99], 0
	s_waitcnt lgkmcnt(0)
	v_cmp_ne_u32_e64 s[26:27], 0, v208
	v_cndmask_b32_e64 v146, v202, v204, s[26:27]
	v_cndmask_b32_e64 v147, v203, v205, s[26:27]
	v_cndmask_b32_e64 v142, v210, v212, s[26:27]
	v_cndmask_b32_e64 v143, v211, v213, s[26:27]
	s_nop 1
	v_mov_b32_e32 v108, v0
	s_nop 5
	v_mov_b32_e32 v109, v16
	s_nop 0
	v_mov_b32_e32 v110, v32
	v_fma_f32 v108, v124, v160, v108
	v_fma_f32 v109, v125, v161, v109
	v_mov_b32_e32 v16, v1
	v_pk_fma_f32 v[108:109], v[130:131], v[176:177], v[108:109] neg_lo:[1,0,0] neg_hi:[1,0,0]
	v_mov_b32_e32 v111, v48
	v_pk_fma_f32 v[110:111], v[124:125], v[176:177], v[110:111]
	v_mov_b32_e32 v48, v33
	v_pk_fma_f32 v[110:111], v[130:131], v[160:161], v[110:111]
	v_mov_b32_e32 v33, v18
	v_cvt_pk_bf16_f32 v0, v108, v110
	ds_write_b32 v163, v0
	v_cvt_pk_bf16_f32 v0, v109, v111
	ds_write_b32 v163, v0 offset:128
	v_pk_fma_f32 v[0:1], v[124:125], v[108:109], v[16:17]
	v_pk_fma_f32 v[16:17], v[124:125], v[110:111], v[48:49]
	v_pk_fma_f32 v[0:1], v[130:131], v[110:111], v[0:1] neg_lo:[1,0,0] neg_hi:[1,0,0]
	v_pk_fma_f32 v[16:17], v[130:131], v[108:109], v[16:17]
	v_mov_b32_e32 v48, v34
	v_cvt_pk_bf16_f32 v32, v0, v16
	ds_write_b32 v163, v32 offset:288
	v_cvt_pk_bf16_f32 v32, v1, v17
	ds_write_b32 v163, v32 offset:416
	v_mov_b32_e32 v32, v2
	v_pk_fma_f32 v[32:33], v[124:125], v[0:1], v[32:33]
	v_mov_b32_e32 v49, v50
	v_pk_fma_f32 v[32:33], v[130:131], v[16:17], v[32:33] neg_lo:[1,0,0] neg_hi:[1,0,0]
	v_pk_fma_f32 v[16:17], v[124:125], v[16:17], v[48:49]
	v_mov_b32_e32 v18, v3
	v_pk_fma_f32 v[0:1], v[130:131], v[0:1], v[16:17]
	v_mov_b32_e32 v50, v35
	v_cvt_pk_bf16_f32 v2, v32, v0
	ds_write_b32 v163, v2 offset:576
	v_cvt_pk_bf16_f32 v2, v33, v1
	ds_write_b32 v163, v2 offset:704
	v_pk_fma_f32 v[2:3], v[124:125], v[32:33], v[18:19]
	v_mov_b32_e32 v17, v20
	v_pk_fma_f32 v[2:3], v[130:131], v[0:1], v[2:3] neg_lo:[1,0,0] neg_hi:[1,0,0]
	v_pk_fma_f32 v[0:1], v[124:125], v[0:1], v[50:51]
	v_mov_b32_e32 v18, v36
	v_pk_fma_f32 v[0:1], v[130:131], v[32:33], v[0:1]
	v_mov_b32_e32 v19, v52
	v_cvt_pk_bf16_f32 v16, v2, v0
	ds_write_b32 v163, v16 offset:864
	v_cvt_pk_bf16_f32 v16, v3, v1
	ds_write_b32 v163, v16 offset:992
	v_mov_b32_e32 v16, v4
	v_pk_fma_f32 v[16:17], v[124:125], v[2:3], v[16:17]
	v_mov_b32_e32 v20, v5
	v_pk_fma_f32 v[16:17], v[130:131], v[0:1], v[16:17] neg_lo:[1,0,0] neg_hi:[1,0,0]
	v_pk_fma_f32 v[0:1], v[124:125], v[0:1], v[18:19]
	v_mov_b32_e32 v52, v37
	v_pk_fma_f32 v[0:1], v[130:131], v[2:3], v[0:1]
	v_mov_b32_e32 v5, v22
	v_cvt_pk_bf16_f32 v2, v16, v0
	ds_write_b32 v163, v2 offset:1152
	v_cvt_pk_bf16_f32 v2, v17, v1
	ds_write_b32 v163, v2 offset:1280
	v_pk_fma_f32 v[2:3], v[124:125], v[16:17], v[20:21]
	v_mov_b32_e32 v22, v7
	v_pk_fma_f32 v[2:3], v[130:131], v[0:1], v[2:3] neg_lo:[1,0,0] neg_hi:[1,0,0]
	v_pk_fma_f32 v[0:1], v[124:125], v[0:1], v[52:53]
	v_mov_b32_e32 v7, v56
	v_pk_fma_f32 v[0:1], v[130:131], v[16:17], v[0:1]
	v_mov_b32_e32 v16, v38
	v_cvt_pk_bf16_f32 v4, v2, v0
	ds_write_b32 v163, v4 offset:1440
	v_cvt_pk_bf16_f32 v4, v3, v1
	ds_write_b32 v163, v4 offset:1568
	v_mov_b32_e32 v4, v6
	v_pk_fma_f32 v[4:5], v[124:125], v[2:3], v[4:5]
	v_mov_b32_e32 v17, v54
	v_pk_fma_f32 v[4:5], v[130:131], v[0:1], v[4:5] neg_lo:[1,0,0] neg_hi:[1,0,0]
	v_pk_fma_f32 v[0:1], v[124:125], v[0:1], v[16:17]
	v_mov_b32_e32 v54, v39
	v_pk_fma_f32 v[0:1], v[130:131], v[2:3], v[0:1]
	v_mov_b32_e32 v6, v40
	v_cvt_pk_bf16_f32 v2, v4, v0
	ds_write_b32 v163, v2 offset:1728
	v_cvt_pk_bf16_f32 v2, v5, v1
	ds_write_b32 v163, v2 offset:1856
	v_pk_fma_f32 v[2:3], v[124:125], v[4:5], v[22:23]
	v_mov_b32_e32 v56, v41
	v_pk_fma_f32 v[2:3], v[130:131], v[0:1], v[2:3] neg_lo:[1,0,0] neg_hi:[1,0,0]
	v_pk_fma_f32 v[0:1], v[124:125], v[0:1], v[54:55]
	s_waitcnt vmcnt(9)
	v_and_b32_e32 v16, 0xffff0000, v145
	v_pk_fma_f32 v[0:1], v[130:131], v[4:5], v[0:1]
	v_mov_b32_e32 v5, v24
	v_cvt_pk_bf16_f32 v4, v2, v0
	ds_write_b32 v163, v4 offset:2016
	v_cvt_pk_bf16_f32 v4, v3, v1
	ds_write_b32 v163, v4 offset:2144
	v_mov_b32_e32 v4, v8
	v_pk_fma_f32 v[4:5], v[124:125], v[2:3], v[4:5]
	v_mov_b32_e32 v24, v9
	v_pk_fma_f32 v[4:5], v[130:131], v[0:1], v[4:5] neg_lo:[1,0,0] neg_hi:[1,0,0]
	v_pk_fma_f32 v[0:1], v[124:125], v[0:1], v[6:7]
	v_mov_b32_e32 v6, v42
	v_pk_fma_f32 v[0:1], v[130:131], v[2:3], v[0:1]
	v_mov_b32_e32 v7, v58
	v_cvt_pk_bf16_f32 v2, v4, v0
	ds_write_b32 v163, v2 offset:2304
	v_cvt_pk_bf16_f32 v2, v5, v1
	ds_write_b32 v163, v2 offset:2432
	v_pk_fma_f32 v[2:3], v[124:125], v[4:5], v[24:25]
	v_mov_b32_e32 v58, v43
	v_pk_fma_f32 v[2:3], v[130:131], v[0:1], v[2:3] neg_lo:[1,0,0] neg_hi:[1,0,0]
	v_pk_fma_f32 v[0:1], v[124:125], v[0:1], v[56:57]
	s_nop 0
	v_pk_fma_f32 v[0:1], v[130:131], v[4:5], v[0:1]
	v_mov_b32_e32 v5, v26
	v_cvt_pk_bf16_f32 v4, v2, v0
	ds_write_b32 v163, v4 offset:2592
	v_cvt_pk_bf16_f32 v4, v3, v1
	ds_write_b32 v163, v4 offset:2720
	v_mov_b32_e32 v4, v10
	v_pk_fma_f32 v[4:5], v[124:125], v[2:3], v[4:5]
	v_mov_b32_e32 v26, v11
	v_pk_fma_f32 v[4:5], v[130:131], v[0:1], v[4:5] neg_lo:[1,0,0] neg_hi:[1,0,0]
	v_pk_fma_f32 v[0:1], v[124:125], v[0:1], v[6:7]
	v_mov_b32_e32 v6, v44
	v_pk_fma_f32 v[0:1], v[130:131], v[2:3], v[0:1]
	v_mov_b32_e32 v7, v60
	v_cvt_pk_bf16_f32 v2, v4, v0
	ds_write_b32 v163, v2 offset:2880
	v_cvt_pk_bf16_f32 v2, v5, v1
	ds_write_b32 v163, v2 offset:3008
	v_pk_fma_f32 v[2:3], v[124:125], v[4:5], v[26:27]
	v_mov_b32_e32 v60, v45
	v_pk_fma_f32 v[2:3], v[130:131], v[0:1], v[2:3] neg_lo:[1,0,0] neg_hi:[1,0,0]
	v_pk_fma_f32 v[0:1], v[124:125], v[0:1], v[58:59]
	s_nop 0
	v_pk_fma_f32 v[0:1], v[130:131], v[4:5], v[0:1]
	v_mov_b32_e32 v5, v28
	v_cvt_pk_bf16_f32 v4, v2, v0
	ds_write_b32 v163, v4 offset:3168
	v_cvt_pk_bf16_f32 v4, v3, v1
	ds_write_b32 v163, v4 offset:3296
	v_mov_b32_e32 v4, v12
	v_pk_fma_f32 v[4:5], v[124:125], v[2:3], v[4:5]
	v_mov_b32_e32 v28, v13
	v_pk_fma_f32 v[4:5], v[130:131], v[0:1], v[4:5] neg_lo:[1,0,0] neg_hi:[1,0,0]
	v_pk_fma_f32 v[0:1], v[124:125], v[0:1], v[6:7]
	v_mov_b32_e32 v6, v46
	v_pk_fma_f32 v[0:1], v[130:131], v[2:3], v[0:1]
	v_mov_b32_e32 v7, v62
	v_cvt_pk_bf16_f32 v2, v4, v0
	ds_write_b32 v163, v2 offset:3456
	v_cvt_pk_bf16_f32 v2, v5, v1
	ds_write_b32 v163, v2 offset:3584
	v_pk_fma_f32 v[2:3], v[124:125], v[4:5], v[28:29]
	v_mov_b32_e32 v62, v47
	v_pk_fma_f32 v[2:3], v[130:131], v[0:1], v[2:3] neg_lo:[1,0,0] neg_hi:[1,0,0]
	v_pk_fma_f32 v[0:1], v[124:125], v[0:1], v[60:61]
	v_pk_mul_f32 v[12:13], v[156:157], v[154:155]
	v_pk_fma_f32 v[0:1], v[130:131], v[4:5], v[0:1]
	v_mov_b32_e32 v5, v30
	v_cvt_pk_bf16_f32 v4, v2, v0
	ds_write_b32 v163, v4 offset:3744
	v_cvt_pk_bf16_f32 v4, v3, v1
	ds_write_b32 v163, v4 offset:3872
	v_mov_b32_e32 v4, v14
	v_pk_fma_f32 v[4:5], v[124:125], v[2:3], v[4:5]
	v_mov_b32_e32 v30, v15
	v_pk_fma_f32 v[4:5], v[130:131], v[0:1], v[4:5] neg_lo:[1,0,0] neg_hi:[1,0,0]
	v_pk_fma_f32 v[0:1], v[124:125], v[0:1], v[6:7]
	v_cvt_pk_bf16_f32 v113, v159, v13
	v_add_co_u32_e32 v14, vcc, s92, v152
	v_pk_fma_f32 v[0:1], v[130:131], v[2:3], v[0:1]
	s_nop 0
	v_addc_co_u32_e32 v15, vcc, 0, v153, vcc
	v_cvt_pk_bf16_f32 v2, v4, v0
	ds_write_b32 v163, v2 offset:4032
	v_cvt_pk_bf16_f32 v2, v5, v1
	ds_write_b32 v163, v2 offset:4160
	v_pk_fma_f32 v[2:3], v[124:125], v[4:5], v[30:31]
	global_store_dwordx2 v[14:15], v[112:113], off
	v_pk_fma_f32 v[108:109], v[130:131], v[0:1], v[2:3] neg_lo:[1,0,0] neg_hi:[1,0,0]
	v_pk_fma_f32 v[0:1], v[124:125], v[0:1], v[62:63]
	v_cvt_pk_bf16_f32 v14, v114, v175
	v_add_u32_e32 v112, v166, v167
	v_pk_fma_f32 v[110:111], v[130:131], v[4:5], v[0:1]
	v_add_u32_e32 v114, 0xe00, v163
	v_cvt_pk_bf16_f32 v0, v108, v110
	ds_write_b32 v163, v0 offset:4320
	v_cvt_pk_bf16_f32 v0, v109, v111
	ds_write_b32 v163, v0 offset:4448
	ds_read_b128 v[0:3], v174
	ds_read_b128 v[4:7], v174 offset:64
	s_waitcnt lgkmcnt(1)
	v_mfma_f32_16x16x32_bf16 v[0:3], v[80:83], v[0:3], 0
	ds_read_b128 v[8:11], v174 offset:128
	v_add_u32_e32 v113, 0x1000, v163
	s_waitcnt lgkmcnt(1)
	v_mfma_f32_16x16x32_bf16 v[0:3], v[76:79], v[4:7], v[0:3]
	ds_read_b128 v[4:7], v174 offset:192
	s_waitcnt lgkmcnt(1)
	v_mfma_f32_16x16x32_bf16 v[0:3], v[72:75], v[8:11], v[0:3]
	v_mul_f32_e32 v8, v12, v13
	v_cvt_pk_bf16_f32 v15, v158, v8
	global_store_dwordx2 v[152:153], v[14:15], off offset:2048
	s_waitcnt lgkmcnt(0)
	v_mfma_f32_16x16x32_bf16 v[0:3], v[68:71], v[4:7], v[0:3]
	v_lshlrev_b32_e32 v4, 16, v146
	v_lshl_add_u64 v[6:7], s[86:87], 0, v[150:151]
	v_lshl_add_u64 v[6:7], v[6:7], 0, s[94:95]
	v_lshl_add_u64 v[12:13], v[6:7], 0, v[120:121]
	v_lshlrev_b32_e32 v6, 16, v147
	s_nop 1
	v_fma_f32 v5, v64, v4, v0
	v_and_b32_e32 v4, 0xffff0000, v146
	v_mul_f32_e32 v0, 0x3d372713, v5
	v_fma_f32 v1, v65, v4, v1
	v_mul_f32_e32 v0, v5, v0
	v_mul_f32_e32 v4, 0x3d372713, v1
	v_fma_f32 v7, v66, v6, v2
	v_fma_f32 v0, v5, v0, v5
	v_mul_f32_e32 v4, v1, v4
	v_mul_f32_e32 v2, 0x3d372713, v7
	v_mul_f32_e32 v0, 0x3fcc422a, v0
	v_fma_f32 v4, v1, v4, v1
	v_mul_f32_e32 v2, v7, v2
	v_mul_f32_e32 v0, 0xbfb8aa3b, v0
	v_mul_f32_e32 v4, 0x3fcc422a, v4
	v_fma_f32 v2, v7, v2, v7
	v_exp_f32_e32 v0, v0
	v_mul_f32_e32 v4, 0xbfb8aa3b, v4
	v_mul_f32_e32 v2, 0x3fcc422a, v2
	v_exp_f32_e32 v4, v4
	v_mul_f32_e32 v2, 0xbfb8aa3b, v2
	v_exp_f32_e32 v2, v2
	v_add_f32_e32 v0, 1.0, v0
	v_rcp_f32_e32 v9, v0
	v_add_f32_e32 v0, 1.0, v4
	v_rcp_f32_e32 v11, v0
	v_add_f32_e32 v0, 1.0, v2
	v_rcp_f32_e32 v15, v0
	v_and_b32_e32 v0, 0xffff0000, v147
	v_fmac_f32_e32 v3, v67, v0
	v_mul_f32_e32 v0, 0x3d372713, v3
	v_mul_f32_e32 v0, v3, v0
	v_fma_f32 v0, v3, v0, v3
	v_mul_f32_e32 v0, 0x3fcc422a, v0
	v_lshlrev_b32_e32 v8, 16, v144
	v_mul_f32_e32 v0, 0xbfb8aa3b, v0
	v_mul_f32_e32 v2, 0xbfb8aa3b, v8
	v_exp_f32_e32 v0, v0
	v_exp_f32_e32 v2, v2
	v_and_b32_e32 v10, 0xffff0000, v144
	v_mul_f32_e32 v4, 0xbfb8aa3b, v10
	v_add_f32_e32 v14, 1.0, v0
	v_add_f32_e32 v0, 1.0, v2
	v_exp_f32_e32 v6, v4
	v_rcp_f32_e32 v4, v0
	v_rcp_f32_e32 v17, v14
	v_lshlrev_b32_e32 v14, 16, v145
	v_mul_f32_e32 v2, 0xbfb8aa3b, v14
	v_exp_f32_e32 v2, v2
	v_add_f32_e32 v0, 1.0, v6
	v_pk_mul_f32 v[4:5], v[4:5], v[8:9]
	v_rcp_f32_e32 v0, v0
	v_mul_f32_e32 v20, v4, v5
	v_mul_f32_e32 v4, 0xbfb8aa3b, v16
	v_exp_f32_e32 v4, v4
	v_add_f32_e32 v2, 1.0, v2
	v_rcp_f32_e32 v6, v2
	v_pk_mul_f32 v[0:1], v[0:1], v[10:11]
	ds_read_b128 v[8:11], v174 offset:4736
	v_mul_f32_e32 v21, v0, v1
	v_add_f32_e32 v0, 1.0, v4
	v_cvt_pk_bf16_f32 v18, v5, v1
	v_rcp_f32_e32 v2, v0
	v_pk_mul_f32 v[0:1], v[6:7], v[14:15]
	ds_read_b128 v[4:7], v174 offset:4608
	v_mul_f32_e32 v22, v0, v1
	v_pk_mul_f32 v[14:15], v[2:3], v[16:17]
	v_add_co_u32_e32 v16, vcc, s92, v12
	v_cvt_pk_bf16_f32 v19, v1, v15
	ds_read_b128 v[0:3], v174 offset:4672
	s_waitcnt lgkmcnt(1)
	v_mfma_f32_16x16x32_bf16 v[4:7], v[80:83], v[4:7], 0
	v_addc_co_u32_e32 v17, vcc, 0, v13, vcc
	global_store_dwordx2 v[16:17], v[18:19], off
	s_waitcnt lgkmcnt(0)
	v_mfma_f32_16x16x32_bf16 v[0:3], v[76:79], v[0:3], v[4:7]
	v_cvt_pk_bf16_f32 v16, v20, v21
	s_nop 3
	ds_read_b128 v[4:7], v174 offset:4800
	v_mfma_f32_16x16x32_bf16 v[0:3], v[72:75], v[8:11], v[0:3]
	v_mul_f32_e32 v8, v14, v15
	v_cvt_pk_bf16_f32 v17, v22, v8
	v_lshlrev_b32_e32 v8, 16, v143
	s_waitcnt lgkmcnt(0)
	v_mfma_f32_16x16x32_bf16 v[0:3], v[68:71], v[4:7], v[0:3]
	v_lshlrev_b32_e32 v4, 16, v142
	global_store_dwordx2 v[12:13], v[16:17], off offset:2048
	s_waitcnt vmcnt(12)
	v_lshlrev_b32_e32 v10, 16, v140
	v_and_b32_e32 v12, 0xffff0000, v140
	v_and_b32_e32 v16, 0xffff0000, v141
	s_nop 1
	v_fma_f32 v5, v64, v4, v0
	v_and_b32_e32 v4, 0xffff0000, v142
	v_mul_f32_e32 v0, 0x3d372713, v5
	v_fma_f32 v1, v65, v4, v1
	v_mul_f32_e32 v0, v5, v0
	v_mul_f32_e32 v4, 0x3d372713, v1
	v_fma_f32 v9, v66, v8, v2
	v_fma_f32 v0, v5, v0, v5
	v_mul_f32_e32 v4, v1, v4
	v_mul_f32_e32 v2, 0x3d372713, v9
	v_mul_f32_e32 v0, 0x3fcc422a, v0
	v_fma_f32 v4, v1, v4, v1
	v_mul_f32_e32 v2, v9, v2
	v_mul_f32_e32 v0, 0xbfb8aa3b, v0
	v_mul_f32_e32 v4, 0x3fcc422a, v4
	v_fma_f32 v2, v9, v2, v9
	v_exp_f32_e32 v0, v0
	v_mul_f32_e32 v4, 0xbfb8aa3b, v4
	v_mul_f32_e32 v2, 0x3fcc422a, v2
	v_exp_f32_e32 v4, v4
	v_mul_f32_e32 v2, 0xbfb8aa3b, v2
	v_exp_f32_e32 v2, v2
	v_add_f32_e32 v0, 1.0, v0
	v_rcp_f32_e32 v11, v0
	v_add_f32_e32 v0, 1.0, v4
	v_rcp_f32_e32 v13, v0
	v_add_f32_e32 v0, 1.0, v2
	v_rcp_f32_e32 v15, v0
	v_and_b32_e32 v0, 0xffff0000, v143
	v_fmac_f32_e32 v3, v67, v0
	v_mul_f32_e32 v0, 0x3d372713, v3
	v_mul_f32_e32 v0, v3, v0
	v_fma_f32 v0, v3, v0, v3
	v_mul_f32_e32 v0, 0x3fcc422a, v0
	v_mul_f32_e32 v0, 0xbfb8aa3b, v0
	v_mul_f32_e32 v2, 0xbfb8aa3b, v10
	v_exp_f32_e32 v0, v0
	v_exp_f32_e32 v2, v2
	v_mul_f32_e32 v4, 0xbfb8aa3b, v12
	v_exp_f32_e32 v8, v4
	v_add_f32_e32 v14, 1.0, v0
	v_add_f32_e32 v0, 1.0, v2
	v_rcp_f32_e32 v4, v0
	v_rcp_f32_e32 v17, v14
	v_lshlrev_b32_e32 v14, 16, v141
	v_mul_f32_e32 v2, 0xbfb8aa3b, v14
	v_pk_mul_f32 v[4:5], v[4:5], v[10:11]
	v_exp_f32_e32 v2, v2
	v_mul_f32_e32 v10, v4, v5
	v_mul_f32_e32 v4, 0xbfb8aa3b, v16
	v_exp_f32_e32 v11, v4
	v_add_f32_e32 v0, 1.0, v8
	v_rcp_f32_e32 v0, v0
	v_add_f32_e32 v2, 1.0, v2
	v_rcp_f32_e32 v8, v2
	v_add_f32_e32 v2, 1.0, v11
	v_lshl_add_u64 v[6:7], s[86:87], 0, v[148:149]
	v_rcp_f32_e32 v2, v2
	v_lshl_add_u64 v[6:7], v[6:7], 0, s[94:95]
	v_pk_mul_f32 v[0:1], v[0:1], v[12:13]
	v_lshl_add_u64 v[6:7], v[6:7], 0, v[120:121]
	v_cvt_pk_bf16_f32 v4, v5, v1
	v_mul_f32_e32 v11, v0, v1
	v_pk_mul_f32 v[0:1], v[8:9], v[14:15]
	v_pk_mul_f32 v[2:3], v[2:3], v[16:17]
	v_mul_f32_e32 v8, v0, v1
	v_add_co_u32_e32 v0, vcc, 0x2000, v6
	v_cvt_pk_bf16_f32 v5, v1, v3
	v_add_u32_e32 v142, 0x400, v163
	s_nop 0
	v_addc_co_u32_e32 v1, vcc, 0, v7, vcc
	global_store_dwordx2 v[0:1], v[4:5], off
	v_mul_f32_e32 v1, v2, v3
	s_and_b64 vcc, exec, s[0:1]
	v_add_u32_e32 v141, 0x600, v163
	v_add_u32_e32 v140, 0x800, v163
	v_cvt_pk_bf16_f32 v0, v10, v11
	v_cvt_pk_bf16_f32 v1, v8, v1
	global_store_dwordx2 v[6:7], v[0:1], off offset:2048
	s_cbranch_vccnz .LBB0_761
	s_waitcnt vmcnt(6)
	ds_bpermute_b32 v202, v206, v104
	ds_bpermute_b32 v203, v206, v105
	ds_bpermute_b32 v204, v206, v106
	ds_bpermute_b32 v205, v206, v107
	ds_bpermute_b32 v210, v207, v104
	ds_bpermute_b32 v211, v207, v105
	ds_bpermute_b32 v212, v207, v106
	ds_bpermute_b32 v213, v207, v107
	v_mfma_f32_32x32x16_bf16 v[48:63], v[104:107], v[84:87], 0
	v_mfma_f32_32x32x16_bf16 v[32:47], v[104:107], v[88:91], 0
	v_mfma_f32_32x32x16_bf16 v[16:31], v[104:107], v[92:95], 0
	v_mfma_f32_32x32x16_bf16 v[0:15], v[104:107], v[96:99], 0
	s_waitcnt lgkmcnt(0)
	v_cmp_ne_u32_e64 s[26:27], 0, v208
	v_cndmask_b32_e64 v138, v202, v204, s[26:27]
	v_cndmask_b32_e64 v139, v203, v205, s[26:27]
	v_cndmask_b32_e64 v134, v210, v212, s[26:27]
	v_cndmask_b32_e64 v135, v211, v213, s[26:27]
	s_nop 8
	v_mov_b32_e32 v104, v48
	v_mov_b32_e32 v105, v32
	v_mov_b32_e32 v106, v16
	v_fma_f32 v104, v124, v108, v104
	v_fma_f32 v105, v125, v109, v105
	v_mov_b32_e32 v32, v49
	v_pk_fma_f32 v[104:105], v[130:131], v[110:111], v[104:105] neg_lo:[1,0,0] neg_hi:[1,0,0]
	v_mov_b32_e32 v48, v18
	v_mov_b32_e32 v107, v0
	v_pk_fma_f32 v[106:107], v[124:125], v[110:111], v[106:107]
	v_pk_fma_f32 v[32:33], v[124:125], v[104:105], v[32:33]
	v_pk_fma_f32 v[106:107], v[130:131], v[108:109], v[106:107]
	v_mov_b32_e32 v49, v2
	v_cvt_pk_bf16_f32 v0, v104, v106
	v_cvt_pk_bf16_f32 v16, v105, v107
	ds_write2_b32 v163, v0, v16 offset1:32
	v_mov_b32_e32 v0, v17
	v_pk_fma_f32 v[0:1], v[124:125], v[106:107], v[0:1]
	v_pk_fma_f32 v[32:33], v[130:131], v[106:107], v[32:33] neg_lo:[1,0,0] neg_hi:[1,0,0]
	v_pk_fma_f32 v[0:1], v[130:131], v[104:105], v[0:1]
	s_nop 0
	v_cvt_pk_bf16_f32 v16, v32, v0
	v_cvt_pk_bf16_f32 v17, v33, v1
	ds_write2_b32 v163, v16, v17 offset0:72 offset1:104
	v_mov_b32_e32 v16, v50
	v_mov_b32_e32 v17, v34
	v_pk_fma_f32 v[16:17], v[124:125], v[32:33], v[16:17]
	v_mov_b32_e32 v34, v51
	v_pk_fma_f32 v[16:17], v[130:131], v[0:1], v[16:17] neg_lo:[1,0,0] neg_hi:[1,0,0]
	v_pk_fma_f32 v[0:1], v[124:125], v[0:1], v[48:49]
	s_nop 0
	v_pk_fma_f32 v[0:1], v[130:131], v[32:33], v[0:1]
	v_pk_fma_f32 v[32:33], v[124:125], v[16:17], v[34:35]
	v_cvt_pk_bf16_f32 v2, v16, v0
	v_cvt_pk_bf16_f32 v18, v17, v1
	ds_write2_b32 v163, v2, v18 offset0:144 offset1:176
	v_mov_b32_e32 v2, v19
	v_pk_fma_f32 v[32:33], v[130:131], v[0:1], v[32:33] neg_lo:[1,0,0] neg_hi:[1,0,0]
	v_pk_fma_f32 v[0:1], v[124:125], v[0:1], v[2:3]
	v_and_b32_e32 v18, 0xffff0000, v137
	v_pk_fma_f32 v[0:1], v[130:131], v[16:17], v[0:1]
	v_mov_b32_e32 v16, v20
	v_cvt_pk_bf16_f32 v2, v32, v0
	v_cvt_pk_bf16_f32 v3, v33, v1
	ds_write2_b32 v163, v2, v3 offset0:216 offset1:248
	v_mov_b32_e32 v2, v52
	v_mov_b32_e32 v3, v36
	v_pk_fma_f32 v[2:3], v[124:125], v[32:33], v[2:3]
	v_mov_b32_e32 v17, v4
	v_pk_fma_f32 v[2:3], v[130:131], v[0:1], v[2:3] neg_lo:[1,0,0] neg_hi:[1,0,0]
	v_pk_fma_f32 v[0:1], v[124:125], v[0:1], v[16:17]
	v_mov_b32_e32 v36, v53
	v_pk_fma_f32 v[0:1], v[130:131], v[32:33], v[0:1]
	s_nop 0
	v_cvt_pk_bf16_f32 v4, v2, v0
	v_cvt_pk_bf16_f32 v16, v3, v1
	ds_write2_b32 v142, v4, v16 offset0:32 offset1:64
	v_mov_b32_e32 v4, v21
	v_pk_fma_f32 v[16:17], v[124:125], v[2:3], v[36:37]
	v_pk_fma_f32 v[4:5], v[124:125], v[0:1], v[4:5]
	v_pk_fma_f32 v[0:1], v[130:131], v[0:1], v[16:17] neg_lo:[1,0,0] neg_hi:[1,0,0]
	v_pk_fma_f32 v[2:3], v[130:131], v[2:3], v[4:5]
	v_mov_b32_e32 v16, v22
	v_cvt_pk_bf16_f32 v4, v0, v2
	v_cvt_pk_bf16_f32 v5, v1, v3
	ds_write2_b32 v142, v4, v5 offset0:104 offset1:136
	v_mov_b32_e32 v4, v54
	v_mov_b32_e32 v5, v38
	v_pk_fma_f32 v[4:5], v[124:125], v[0:1], v[4:5]
	v_mov_b32_e32 v17, v6
	v_pk_fma_f32 v[4:5], v[130:131], v[2:3], v[4:5] neg_lo:[1,0,0] neg_hi:[1,0,0]
	v_pk_fma_f32 v[2:3], v[124:125], v[2:3], v[16:17]
	v_mov_b32_e32 v38, v55
	v_pk_fma_f32 v[0:1], v[130:131], v[0:1], v[2:3]
	v_mov_b32_e32 v6, v23
	v_cvt_pk_bf16_f32 v2, v4, v0
	v_cvt_pk_bf16_f32 v3, v5, v1
	ds_write2_b32 v142, v2, v3 offset0:176 offset1:208
	v_pk_fma_f32 v[2:3], v[124:125], v[4:5], v[38:39]
	v_lshlrev_b32_e32 v16, 16, v137
	v_pk_fma_f32 v[2:3], v[130:131], v[0:1], v[2:3] neg_lo:[1,0,0] neg_hi:[1,0,0]
	v_pk_fma_f32 v[0:1], v[124:125], v[0:1], v[6:7]
	v_mov_b32_e32 v6, v24
	v_pk_fma_f32 v[0:1], v[130:131], v[4:5], v[0:1]
	v_mov_b32_e32 v7, v8
	v_cvt_pk_bf16_f32 v4, v2, v0
	v_cvt_pk_bf16_f32 v5, v3, v1
	ds_write2_b32 v141, v4, v5 offset0:120 offset1:152
	v_mov_b32_e32 v4, v56
	v_mov_b32_e32 v5, v40
	v_pk_fma_f32 v[4:5], v[124:125], v[2:3], v[4:5]
	v_mov_b32_e32 v40, v57
	v_pk_fma_f32 v[4:5], v[130:131], v[0:1], v[4:5] neg_lo:[1,0,0] neg_hi:[1,0,0]
	v_pk_fma_f32 v[0:1], v[124:125], v[0:1], v[6:7]
	v_mov_b32_e32 v8, v25
	v_pk_fma_f32 v[0:1], v[130:131], v[2:3], v[0:1]
	v_mov_b32_e32 v6, v26
	v_cvt_pk_bf16_f32 v2, v4, v0
	v_cvt_pk_bf16_f32 v3, v5, v1
	ds_write2_b32 v140, v2, v3 offset0:64 offset1:96
	v_pk_fma_f32 v[2:3], v[124:125], v[4:5], v[40:41]
	v_mov_b32_e32 v7, v10
	v_pk_fma_f32 v[2:3], v[130:131], v[0:1], v[2:3] neg_lo:[1,0,0] neg_hi:[1,0,0]
	v_pk_fma_f32 v[0:1], v[124:125], v[0:1], v[8:9]
	v_mov_b32_e32 v10, v27
	v_pk_fma_f32 v[0:1], v[130:131], v[4:5], v[0:1]
	v_lshlrev_b32_e32 v8, 16, v138
	v_cvt_pk_bf16_f32 v4, v2, v0
	v_cvt_pk_bf16_f32 v5, v3, v1
	ds_write2_b32 v140, v4, v5 offset0:136 offset1:168
	v_mov_b32_e32 v4, v58
	v_mov_b32_e32 v5, v42
	v_pk_fma_f32 v[4:5], v[124:125], v[2:3], v[4:5]
	v_mov_b32_e32 v42, v59
	v_pk_fma_f32 v[4:5], v[130:131], v[0:1], v[4:5] neg_lo:[1,0,0] neg_hi:[1,0,0]
	v_pk_fma_f32 v[0:1], v[124:125], v[0:1], v[6:7]
	v_mov_b32_e32 v6, v28
	v_pk_fma_f32 v[0:1], v[130:131], v[2:3], v[0:1]
	v_mov_b32_e32 v7, v12
	v_cvt_pk_bf16_f32 v2, v4, v0
	v_cvt_pk_bf16_f32 v3, v5, v1
	ds_write2_b32 v140, v2, v3 offset0:208 offset1:240
	v_pk_fma_f32 v[2:3], v[124:125], v[4:5], v[42:43]
	v_mov_b32_e32 v12, v29
	v_pk_fma_f32 v[2:3], v[130:131], v[0:1], v[2:3] neg_lo:[1,0,0] neg_hi:[1,0,0]
	v_pk_fma_f32 v[0:1], v[124:125], v[0:1], v[10:11]
	v_lshlrev_b32_e32 v10, 16, v136
	v_pk_fma_f32 v[0:1], v[130:131], v[4:5], v[0:1]
	s_nop 0
	v_cvt_pk_bf16_f32 v4, v2, v0
	v_cvt_pk_bf16_f32 v5, v3, v1
	ds_write2_b32 v115, v4, v5 offset0:24 offset1:56
	v_mov_b32_e32 v4, v60
	v_mov_b32_e32 v5, v44
	v_pk_fma_f32 v[4:5], v[124:125], v[2:3], v[4:5]
	v_mov_b32_e32 v44, v61
	v_pk_fma_f32 v[4:5], v[130:131], v[0:1], v[4:5] neg_lo:[1,0,0] neg_hi:[1,0,0]
	v_pk_fma_f32 v[0:1], v[124:125], v[0:1], v[6:7]
	v_mov_b32_e32 v6, v30
	v_pk_fma_f32 v[0:1], v[130:131], v[2:3], v[0:1]
	v_mov_b32_e32 v7, v14
	v_cvt_pk_bf16_f32 v2, v4, v0
	v_cvt_pk_bf16_f32 v3, v5, v1
	ds_write2_b32 v115, v2, v3 offset0:96 offset1:128
	v_pk_fma_f32 v[2:3], v[124:125], v[4:5], v[44:45]
	v_mov_b32_e32 v14, v31
	v_pk_fma_f32 v[2:3], v[130:131], v[0:1], v[2:3] neg_lo:[1,0,0] neg_hi:[1,0,0]
	v_pk_fma_f32 v[0:1], v[124:125], v[0:1], v[12:13]
	v_and_b32_e32 v12, 0xffff0000, v136
	v_pk_fma_f32 v[0:1], v[130:131], v[4:5], v[0:1]
	s_nop 0
	v_cvt_pk_bf16_f32 v4, v2, v0
	v_cvt_pk_bf16_f32 v5, v3, v1
	ds_write2_b32 v115, v4, v5 offset0:168 offset1:200
	v_mov_b32_e32 v4, v62
	v_mov_b32_e32 v5, v46
	v_pk_fma_f32 v[4:5], v[124:125], v[2:3], v[4:5]
	v_mov_b32_e32 v46, v63
	v_pk_fma_f32 v[4:5], v[130:131], v[0:1], v[4:5] neg_lo:[1,0,0] neg_hi:[1,0,0]
	v_pk_fma_f32 v[0:1], v[124:125], v[0:1], v[6:7]
	s_nop 0
	v_pk_fma_f32 v[0:1], v[130:131], v[2:3], v[0:1]
	s_nop 0
	v_cvt_pk_bf16_f32 v2, v4, v0
	v_cvt_pk_bf16_f32 v3, v5, v1
	ds_write2_b32 v114, v2, v3 offset0:112 offset1:144
	v_pk_fma_f32 v[2:3], v[124:125], v[4:5], v[46:47]
	s_nop 0
	v_pk_fma_f32 v[108:109], v[130:131], v[0:1], v[2:3] neg_lo:[1,0,0] neg_hi:[1,0,0]
	v_pk_fma_f32 v[0:1], v[124:125], v[0:1], v[14:15]
	s_nop 0
	v_pk_fma_f32 v[110:111], v[130:131], v[4:5], v[0:1]
	s_nop 0
	v_cvt_pk_bf16_f32 v0, v108, v110
	v_cvt_pk_bf16_f32 v1, v109, v111
	ds_write2_b32 v113, v0, v1 offset0:56 offset1:88
	ds_read_b128 v[0:3], v112
	ds_read_b128 v[4:7], v112 offset:64
	s_waitcnt lgkmcnt(1)
	v_mfma_f32_16x16x32_bf16 v[0:3], v[80:83], v[0:3], 0
	s_waitcnt lgkmcnt(0)
	v_mfma_f32_16x16x32_bf16 v[0:3], v[76:79], v[4:7], v[0:3]
	ds_read_b128 v[4:7], v112 offset:128
	s_waitcnt lgkmcnt(0)
	v_mfma_f32_16x16x32_bf16 v[0:3], v[72:75], v[4:7], v[0:3]
	ds_read_b128 v[4:7], v112 offset:192
	s_waitcnt lgkmcnt(0)
	v_mfma_f32_16x16x32_bf16 v[2:5], v[68:71], v[4:7], v[0:3]
	s_nop 4
	v_mov_b64_e32 v[0:1], s[86:87]
	v_mad_i64_i32 v[6:7], s[22:23], v165, s66, v[0:1]
	s_nop 0
	v_fma_f32 v9, v64, v8, v2
	v_mul_f32_e32 v2, 0x3d372713, v9
	v_mul_f32_e32 v2, v9, v2
	v_fma_f32 v2, v9, v2, v9
	v_mul_f32_e32 v2, 0x3fcc422a, v2
	v_mul_f32_e32 v2, 0xbfb8aa3b, v2
	v_exp_f32_e32 v2, v2
	v_lshl_add_u64 v[6:7], v[6:7], 0, s[94:95]
	v_lshl_add_u64 v[6:7], v[6:7], 0, v[120:121]
	v_mad_i64_i32 v[0:1], s[22:23], v164, s66, v[0:1]
	v_add_f32_e32 v2, 1.0, v2
	v_rcp_f32_e32 v11, v2
	v_and_b32_e32 v2, 0xffff0000, v138
	v_fma_f32 v3, v65, v2, v3
	v_mul_f32_e32 v2, 0x3d372713, v3
	v_mul_f32_e32 v2, v3, v2
	v_fma_f32 v2, v3, v2, v3
	v_mul_f32_e32 v2, 0x3fcc422a, v2
	v_mul_f32_e32 v2, 0xbfb8aa3b, v2
	v_exp_f32_e32 v2, v2
	v_lshl_add_u64 v[0:1], v[0:1], 0, s[94:95]
	v_lshl_add_u64 v[0:1], v[0:1], 0, v[120:121]
	v_add_f32_e32 v2, 1.0, v2
	v_rcp_f32_e32 v13, v2
	v_lshlrev_b32_e32 v2, 16, v139
	v_fma_f32 v15, v66, v2, v4
	v_mul_f32_e32 v2, 0x3d372713, v15
	v_mul_f32_e32 v2, v15, v2
	v_fma_f32 v2, v15, v2, v15
	v_mul_f32_e32 v2, 0x3fcc422a, v2
	v_mul_f32_e32 v2, 0xbfb8aa3b, v2
	v_exp_f32_e32 v2, v2
	s_nop 0
	v_add_f32_e32 v2, 1.0, v2
	v_rcp_f32_e32 v17, v2
	v_and_b32_e32 v2, 0xffff0000, v139
	v_fmac_f32_e32 v5, v67, v2
	v_mul_f32_e32 v2, 0x3d372713, v5
	v_mul_f32_e32 v2, v5, v2
	v_fma_f32 v2, v5, v2, v5
	v_mul_f32_e32 v2, 0x3fcc422a, v2
	v_mul_f32_e32 v2, 0xbfb8aa3b, v2
	v_exp_f32_e32 v2, v2
	s_nop 0
	v_add_f32_e32 v2, 1.0, v2
	v_rcp_f32_e32 v19, v2
	v_mul_f32_e32 v2, 0xbfb8aa3b, v10
	v_exp_f32_e32 v2, v2
	s_nop 0
	v_add_f32_e32 v2, 1.0, v2
	v_rcp_f32_e32 v8, v2
	v_mul_f32_e32 v2, 0xbfb8aa3b, v12
	v_exp_f32_e32 v2, v2
	v_pk_mul_f32 v[8:9], v[8:9], v[10:11]
	s_nop 0
	v_mul_f32_e32 v10, v8, v9
	v_add_f32_e32 v2, 1.0, v2
	v_rcp_f32_e32 v2, v2
	s_nop 0
	v_pk_mul_f32 v[2:3], v[2:3], v[12:13]
	s_nop 0
	v_mul_f32_e32 v11, v2, v3
	v_mul_f32_e32 v2, 0xbfb8aa3b, v16
	v_exp_f32_e32 v2, v2
	v_cvt_pk_bf16_f32 v8, v9, v3
	s_nop 0
	v_add_f32_e32 v2, 1.0, v2
	v_rcp_f32_e32 v14, v2
	s_nop 0
	v_pk_mul_f32 v[2:3], v[14:15], v[16:17]
	s_nop 0
	v_mul_f32_e32 v12, v2, v3
	v_mul_f32_e32 v2, 0xbfb8aa3b, v18
	v_exp_f32_e32 v2, v2
	v_lshlrev_b32_e32 v14, 16, v133
	v_and_b32_e32 v16, 0xffff0000, v133
	v_add_f32_e32 v2, 1.0, v2
	v_rcp_f32_e32 v4, v2
	v_add_co_u32_e32 v2, vcc, s92, v6
	v_pk_mul_f32 v[4:5], v[4:5], v[18:19]
	s_nop 0
	v_cvt_pk_bf16_f32 v9, v3, v5
	v_addc_co_u32_e32 v3, vcc, 0, v7, vcc
	global_store_dwordx2 v[2:3], v[8:9], off
	v_mul_f32_e32 v3, v4, v5
	v_cvt_pk_bf16_f32 v2, v10, v11
	v_cvt_pk_bf16_f32 v3, v12, v3
	global_store_dwordx2 v[6:7], v[2:3], off offset:2048
	ds_read_b128 v[2:5], v112 offset:4608
	ds_read_b128 v[6:9], v112 offset:4672
	s_waitcnt lgkmcnt(1)
	v_mfma_f32_16x16x32_bf16 v[2:5], v[80:83], v[2:5], 0
	v_and_b32_e32 v10, 0xffff0000, v132
	s_waitcnt lgkmcnt(0)
	v_mfma_f32_16x16x32_bf16 v[2:5], v[76:79], v[6:9], v[2:5]
	ds_read_b128 v[6:9], v112 offset:4736
	s_waitcnt lgkmcnt(0)
	v_mfma_f32_16x16x32_bf16 v[2:5], v[72:75], v[6:9], v[2:5]
	ds_read_b128 v[6:9], v112 offset:4800
	s_waitcnt lgkmcnt(0)
	v_mfma_f32_16x16x32_bf16 v[2:5], v[68:71], v[6:9], v[2:5]
	v_lshlrev_b32_e32 v6, 16, v134
	v_lshlrev_b32_e32 v8, 16, v132
	s_nop 5
	v_fma_f32 v7, v64, v6, v2
	v_mul_f32_e32 v2, 0x3d372713, v7
	v_mul_f32_e32 v2, v7, v2
	v_fma_f32 v2, v7, v2, v7
	v_mul_f32_e32 v2, 0x3fcc422a, v2
	v_mul_f32_e32 v2, 0xbfb8aa3b, v2
	v_exp_f32_e32 v2, v2
	s_nop 0
	v_add_f32_e32 v2, 1.0, v2
	v_rcp_f32_e32 v9, v2
	v_and_b32_e32 v2, 0xffff0000, v134
	v_fma_f32 v3, v65, v2, v3
	v_mul_f32_e32 v2, 0x3d372713, v3
	v_mul_f32_e32 v2, v3, v2
	v_fma_f32 v2, v3, v2, v3
	v_mul_f32_e32 v2, 0x3fcc422a, v2
	v_mul_f32_e32 v2, 0xbfb8aa3b, v2
	v_exp_f32_e32 v2, v2
	s_nop 0
	v_add_f32_e32 v2, 1.0, v2
	v_rcp_f32_e32 v11, v2
	v_lshlrev_b32_e32 v2, 16, v135
	v_fma_f32 v13, v66, v2, v4
	v_mul_f32_e32 v2, 0x3d372713, v13
	v_mul_f32_e32 v2, v13, v2
	v_fma_f32 v2, v13, v2, v13
	v_mul_f32_e32 v2, 0x3fcc422a, v2
	v_mul_f32_e32 v2, 0xbfb8aa3b, v2
	v_exp_f32_e32 v2, v2
	s_nop 0
	v_add_f32_e32 v2, 1.0, v2
	v_rcp_f32_e32 v15, v2
	v_and_b32_e32 v2, 0xffff0000, v135
	v_fmac_f32_e32 v5, v67, v2
	v_mul_f32_e32 v2, 0x3d372713, v5
	v_mul_f32_e32 v2, v5, v2
	v_fma_f32 v2, v5, v2, v5
	v_mul_f32_e32 v2, 0x3fcc422a, v2
	v_mul_f32_e32 v2, 0xbfb8aa3b, v2
	v_exp_f32_e32 v2, v2
	s_nop 0
	v_add_f32_e32 v2, 1.0, v2
	v_rcp_f32_e32 v17, v2
	v_mul_f32_e32 v2, 0xbfb8aa3b, v8
	v_exp_f32_e32 v2, v2
	s_nop 0
	v_add_f32_e32 v2, 1.0, v2
	v_rcp_f32_e32 v6, v2
	v_mul_f32_e32 v2, 0xbfb8aa3b, v10
	v_exp_f32_e32 v2, v2
	v_pk_mul_f32 v[6:7], v[6:7], v[8:9]
	s_nop 0
	v_mul_f32_e32 v8, v6, v7
	v_add_f32_e32 v2, 1.0, v2
	v_rcp_f32_e32 v2, v2
	s_nop 0
	v_pk_mul_f32 v[2:3], v[2:3], v[10:11]
	s_nop 0
	v_mul_f32_e32 v9, v2, v3
	v_mul_f32_e32 v2, 0xbfb8aa3b, v14
	v_exp_f32_e32 v2, v2
	v_cvt_pk_bf16_f32 v6, v7, v3
	s_nop 0
	v_add_f32_e32 v2, 1.0, v2
	v_rcp_f32_e32 v12, v2
	s_nop 0
	v_pk_mul_f32 v[2:3], v[12:13], v[14:15]
	s_nop 0
	v_mul_f32_e32 v10, v2, v3
	v_mul_f32_e32 v2, 0xbfb8aa3b, v16
	v_exp_f32_e32 v2, v2
	s_nop 0
	v_add_f32_e32 v2, 1.0, v2
	v_rcp_f32_e32 v4, v2
	v_add_co_u32_e32 v2, vcc, 0x2000, v0
	v_pk_mul_f32 v[4:5], v[4:5], v[16:17]
	s_nop 0
	v_cvt_pk_bf16_f32 v7, v3, v5
	v_addc_co_u32_e32 v3, vcc, 0, v1, vcc
	global_store_dwordx2 v[2:3], v[6:7], off
	v_mul_f32_e32 v3, v4, v5
	v_cvt_pk_bf16_f32 v2, v8, v9
	v_cvt_pk_bf16_f32 v3, v10, v3
	global_store_dwordx2 v[0:1], v[2:3], off offset:2048
	s_and_b64 vcc, exec, s[0:1]
	s_cbranch_vccz .LBB0_762

.LBB0_762:
	ds_bpermute_b32 v202, v206, v100
	ds_bpermute_b32 v203, v206, v101
	ds_bpermute_b32 v204, v206, v102
	ds_bpermute_b32 v205, v206, v103
	ds_bpermute_b32 v210, v207, v100
	ds_bpermute_b32 v211, v207, v101
	ds_bpermute_b32 v212, v207, v102
	ds_bpermute_b32 v213, v207, v103
	v_mfma_f32_32x32x16_bf16 v[48:63], v[100:103], v[84:87], 0
	v_mov_b32_e32 v121, v173
	v_mfma_f32_32x32x16_bf16 v[32:47], v[100:103], v[88:91], 0
	s_nop 9
	v_mov_b32_e32 v84, v48
	v_mfma_f32_32x32x16_bf16 v[16:31], v[100:103], v[92:95], 0
	v_mov_b32_e32 v85, v32
	v_fma_f32 v84, v124, v108, v84
	v_fma_f32 v85, v125, v109, v85
	v_mov_b32_e32 v32, v49
	v_fma_f32 v84, -v130, v110, v84
	v_fma_f32 v85, -v131, v111, v85
	v_pk_fma_f32 v[32:33], v[124:125], v[84:85], v[32:33]
	s_nop 4
	v_mov_b32_e32 v86, v16
	v_mfma_f32_32x32x16_bf16 v[0:15], v[100:103], v[96:99], 0
	s_waitcnt lgkmcnt(0)
	v_cmp_ne_u32_e64 s[26:27], 0, v208
	v_cndmask_b32_e64 v128, v202, v204, s[26:27]
	v_cndmask_b32_e64 v129, v203, v205, s[26:27]
	v_cndmask_b32_e64 v122, v210, v212, s[26:27]
	v_cndmask_b32_e64 v123, v211, v213, s[26:27]
	v_mov_b32_e32 v48, v18
	s_nop 10
	v_mov_b32_e32 v87, v0
	v_pk_fma_f32 v[86:87], v[124:125], v[110:111], v[86:87]
	v_mov_b32_e32 v49, v2
	v_pk_fma_f32 v[86:87], v[130:131], v[108:109], v[86:87]
	s_nop 0
	v_cvt_pk_bf16_f32 v0, v84, v86
	v_cvt_pk_bf16_f32 v16, v85, v87
	ds_write2_b32 v163, v0, v16 offset1:32
	v_mov_b32_e32 v0, v17
	v_pk_fma_f32 v[0:1], v[124:125], v[86:87], v[0:1]
	v_pk_fma_f32 v[32:33], v[130:131], v[86:87], v[32:33] neg_lo:[1,0,0] neg_hi:[1,0,0]
	v_pk_fma_f32 v[0:1], v[130:131], v[84:85], v[0:1]
	s_nop 0
	v_cvt_pk_bf16_f32 v16, v32, v0
	v_cvt_pk_bf16_f32 v17, v33, v1
	ds_write2_b32 v163, v16, v17 offset0:72 offset1:104
	v_mov_b32_e32 v16, v50
	v_mov_b32_e32 v17, v34
	v_pk_fma_f32 v[16:17], v[124:125], v[32:33], v[16:17]
	v_mov_b32_e32 v34, v51
	v_pk_fma_f32 v[16:17], v[130:131], v[0:1], v[16:17] neg_lo:[1,0,0] neg_hi:[1,0,0]
	v_pk_fma_f32 v[0:1], v[124:125], v[0:1], v[48:49]
	s_nop 0
	v_pk_fma_f32 v[0:1], v[130:131], v[32:33], v[0:1]
	v_pk_fma_f32 v[32:33], v[124:125], v[16:17], v[34:35]
	v_cvt_pk_bf16_f32 v2, v16, v0
	v_cvt_pk_bf16_f32 v18, v17, v1
	ds_write2_b32 v163, v2, v18 offset0:144 offset1:176
	v_mov_b32_e32 v2, v19
	v_pk_fma_f32 v[32:33], v[130:131], v[0:1], v[32:33] neg_lo:[1,0,0] neg_hi:[1,0,0]
	v_pk_fma_f32 v[0:1], v[124:125], v[0:1], v[2:3]
	v_and_b32_e32 v18, 0xffff0000, v127
	v_pk_fma_f32 v[0:1], v[130:131], v[16:17], v[0:1]
	v_mov_b32_e32 v16, v20
	v_cvt_pk_bf16_f32 v2, v32, v0
	v_cvt_pk_bf16_f32 v3, v33, v1
	ds_write2_b32 v163, v2, v3 offset0:216 offset1:248
	v_mov_b32_e32 v2, v52
	v_mov_b32_e32 v3, v36
	v_pk_fma_f32 v[2:3], v[124:125], v[32:33], v[2:3]
	v_mov_b32_e32 v17, v4
	v_pk_fma_f32 v[2:3], v[130:131], v[0:1], v[2:3] neg_lo:[1,0,0] neg_hi:[1,0,0]
	v_pk_fma_f32 v[0:1], v[124:125], v[0:1], v[16:17]
	v_mov_b32_e32 v36, v53
	v_pk_fma_f32 v[0:1], v[130:131], v[32:33], v[0:1]
	s_nop 0
	v_cvt_pk_bf16_f32 v4, v2, v0
	v_cvt_pk_bf16_f32 v16, v3, v1
	ds_write2_b32 v142, v4, v16 offset0:32 offset1:64
	v_mov_b32_e32 v4, v21
	v_pk_fma_f32 v[16:17], v[124:125], v[2:3], v[36:37]
	v_pk_fma_f32 v[4:5], v[124:125], v[0:1], v[4:5]
	v_pk_fma_f32 v[0:1], v[130:131], v[0:1], v[16:17] neg_lo:[1,0,0] neg_hi:[1,0,0]
	v_pk_fma_f32 v[2:3], v[130:131], v[2:3], v[4:5]
	v_mov_b32_e32 v16, v22
	v_cvt_pk_bf16_f32 v4, v0, v2
	v_cvt_pk_bf16_f32 v5, v1, v3
	ds_write2_b32 v142, v4, v5 offset0:104 offset1:136
	v_mov_b32_e32 v4, v54
	v_mov_b32_e32 v5, v38
	v_pk_fma_f32 v[4:5], v[124:125], v[0:1], v[4:5]
	v_mov_b32_e32 v17, v6
	v_pk_fma_f32 v[4:5], v[130:131], v[2:3], v[4:5] neg_lo:[1,0,0] neg_hi:[1,0,0]
	v_pk_fma_f32 v[2:3], v[124:125], v[2:3], v[16:17]
	v_mov_b32_e32 v38, v55
	v_pk_fma_f32 v[0:1], v[130:131], v[0:1], v[2:3]
	v_mov_b32_e32 v6, v23
	v_cvt_pk_bf16_f32 v2, v4, v0
	v_cvt_pk_bf16_f32 v3, v5, v1
	ds_write2_b32 v142, v2, v3 offset0:176 offset1:208
	v_pk_fma_f32 v[2:3], v[124:125], v[4:5], v[38:39]
	v_lshlrev_b32_e32 v16, 16, v127
	v_pk_fma_f32 v[2:3], v[130:131], v[0:1], v[2:3] neg_lo:[1,0,0] neg_hi:[1,0,0]
	v_pk_fma_f32 v[0:1], v[124:125], v[0:1], v[6:7]
	v_mov_b32_e32 v6, v24
	v_pk_fma_f32 v[0:1], v[130:131], v[4:5], v[0:1]
	v_mov_b32_e32 v7, v8
	v_cvt_pk_bf16_f32 v4, v2, v0
	v_cvt_pk_bf16_f32 v5, v3, v1
	ds_write2_b32 v141, v4, v5 offset0:120 offset1:152
	v_mov_b32_e32 v4, v56
	v_mov_b32_e32 v5, v40
	v_pk_fma_f32 v[4:5], v[124:125], v[2:3], v[4:5]
	v_mov_b32_e32 v40, v57
	v_pk_fma_f32 v[4:5], v[130:131], v[0:1], v[4:5] neg_lo:[1,0,0] neg_hi:[1,0,0]
	v_pk_fma_f32 v[0:1], v[124:125], v[0:1], v[6:7]
	v_mov_b32_e32 v8, v25
	v_pk_fma_f32 v[0:1], v[130:131], v[2:3], v[0:1]
	v_mov_b32_e32 v6, v26
	v_cvt_pk_bf16_f32 v2, v4, v0
	v_cvt_pk_bf16_f32 v3, v5, v1
	ds_write2_b32 v140, v2, v3 offset0:64 offset1:96
	v_pk_fma_f32 v[2:3], v[124:125], v[4:5], v[40:41]
	v_mov_b32_e32 v7, v10
	v_pk_fma_f32 v[2:3], v[130:131], v[0:1], v[2:3] neg_lo:[1,0,0] neg_hi:[1,0,0]
	v_pk_fma_f32 v[0:1], v[124:125], v[0:1], v[8:9]
	v_mov_b32_e32 v10, v27
	v_pk_fma_f32 v[0:1], v[130:131], v[4:5], v[0:1]
	v_lshlrev_b32_e32 v8, 16, v128
	v_cvt_pk_bf16_f32 v4, v2, v0
	v_cvt_pk_bf16_f32 v5, v3, v1
	ds_write2_b32 v140, v4, v5 offset0:136 offset1:168
	v_mov_b32_e32 v4, v58
	v_mov_b32_e32 v5, v42
	v_pk_fma_f32 v[4:5], v[124:125], v[2:3], v[4:5]
	v_mov_b32_e32 v42, v59
	v_pk_fma_f32 v[4:5], v[130:131], v[0:1], v[4:5] neg_lo:[1,0,0] neg_hi:[1,0,0]
	v_pk_fma_f32 v[0:1], v[124:125], v[0:1], v[6:7]
	v_mov_b32_e32 v6, v28
	v_pk_fma_f32 v[0:1], v[130:131], v[2:3], v[0:1]
	v_mov_b32_e32 v7, v12
	v_cvt_pk_bf16_f32 v2, v4, v0
	v_cvt_pk_bf16_f32 v3, v5, v1
	ds_write2_b32 v140, v2, v3 offset0:208 offset1:240
	v_pk_fma_f32 v[2:3], v[124:125], v[4:5], v[42:43]
	v_mov_b32_e32 v12, v29
	v_pk_fma_f32 v[2:3], v[130:131], v[0:1], v[2:3] neg_lo:[1,0,0] neg_hi:[1,0,0]
	v_pk_fma_f32 v[0:1], v[124:125], v[0:1], v[10:11]
	v_lshlrev_b32_e32 v10, 16, v126
	v_pk_fma_f32 v[0:1], v[130:131], v[4:5], v[0:1]
	s_nop 0
	v_cvt_pk_bf16_f32 v4, v2, v0
	v_cvt_pk_bf16_f32 v5, v3, v1
	ds_write2_b32 v115, v4, v5 offset0:24 offset1:56
	v_mov_b32_e32 v4, v60
	v_mov_b32_e32 v5, v44
	v_pk_fma_f32 v[4:5], v[124:125], v[2:3], v[4:5]
	v_mov_b32_e32 v44, v61
	v_pk_fma_f32 v[4:5], v[130:131], v[0:1], v[4:5] neg_lo:[1,0,0] neg_hi:[1,0,0]
	v_pk_fma_f32 v[0:1], v[124:125], v[0:1], v[6:7]
	v_mov_b32_e32 v6, v30
	v_pk_fma_f32 v[0:1], v[130:131], v[2:3], v[0:1]
	v_mov_b32_e32 v7, v14
	v_cvt_pk_bf16_f32 v2, v4, v0
	v_cvt_pk_bf16_f32 v3, v5, v1
	ds_write2_b32 v115, v2, v3 offset0:96 offset1:128
	v_pk_fma_f32 v[2:3], v[124:125], v[4:5], v[44:45]
	v_mov_b32_e32 v14, v31
	v_pk_fma_f32 v[2:3], v[130:131], v[0:1], v[2:3] neg_lo:[1,0,0] neg_hi:[1,0,0]
	v_pk_fma_f32 v[0:1], v[124:125], v[0:1], v[12:13]
	v_and_b32_e32 v12, 0xffff0000, v126
	v_pk_fma_f32 v[0:1], v[130:131], v[4:5], v[0:1]
	s_nop 0
	v_cvt_pk_bf16_f32 v4, v2, v0
	v_cvt_pk_bf16_f32 v5, v3, v1
	ds_write2_b32 v115, v4, v5 offset0:168 offset1:200
	v_mov_b32_e32 v4, v62
	v_mov_b32_e32 v5, v46
	v_pk_fma_f32 v[4:5], v[124:125], v[2:3], v[4:5]
	v_mov_b32_e32 v46, v63
	v_pk_fma_f32 v[4:5], v[130:131], v[0:1], v[4:5] neg_lo:[1,0,0] neg_hi:[1,0,0]
	v_pk_fma_f32 v[0:1], v[124:125], v[0:1], v[6:7]
	s_nop 0
	v_pk_fma_f32 v[0:1], v[130:131], v[2:3], v[0:1]
	s_nop 0
	v_cvt_pk_bf16_f32 v2, v4, v0
	v_cvt_pk_bf16_f32 v3, v5, v1
	ds_write2_b32 v114, v2, v3 offset0:112 offset1:144
	v_pk_fma_f32 v[2:3], v[124:125], v[4:5], v[46:47]
	s_nop 0
	v_pk_fma_f32 v[108:109], v[130:131], v[0:1], v[2:3] neg_lo:[1,0,0] neg_hi:[1,0,0]
	v_pk_fma_f32 v[0:1], v[124:125], v[0:1], v[14:15]
	s_nop 0
	v_pk_fma_f32 v[110:111], v[130:131], v[4:5], v[0:1]
	s_nop 0
	v_cvt_pk_bf16_f32 v0, v108, v110
	v_cvt_pk_bf16_f32 v1, v109, v111
	ds_write2_b32 v113, v0, v1 offset0:56 offset1:88
	ds_read_b128 v[0:3], v112
	ds_read_b128 v[4:7], v112 offset:64
	s_waitcnt lgkmcnt(1)
	v_mfma_f32_16x16x32_bf16 v[0:3], v[80:83], v[0:3], 0
	s_waitcnt lgkmcnt(0)
	v_mfma_f32_16x16x32_bf16 v[0:3], v[76:79], v[4:7], v[0:3]
	ds_read_b128 v[4:7], v112 offset:128
	s_waitcnt lgkmcnt(0)
	v_mfma_f32_16x16x32_bf16 v[0:3], v[72:75], v[4:7], v[0:3]
	ds_read_b128 v[4:7], v112 offset:192
	s_waitcnt lgkmcnt(0)
	v_mfma_f32_16x16x32_bf16 v[2:5], v[68:71], v[4:7], v[0:3]
	s_nop 4
	v_mov_b64_e32 v[0:1], s[86:87]
	v_mad_i64_i32 v[6:7], s[0:1], v162, s66, v[0:1]
	s_nop 0
	v_fma_f32 v9, v64, v8, v2
	v_mul_f32_e32 v2, 0x3d372713, v9
	v_mul_f32_e32 v2, v9, v2
	v_fma_f32 v2, v9, v2, v9
	v_mul_f32_e32 v2, 0x3fcc422a, v2
	v_mul_f32_e32 v2, 0xbfb8aa3b, v2
	v_exp_f32_e32 v2, v2
	v_lshl_add_u64 v[6:7], v[6:7], 0, s[94:95]
	v_lshl_add_u64 v[6:7], v[6:7], 0, v[120:121]
	v_mad_i64_i32 v[0:1], s[0:1], v117, s66, v[0:1]
	v_add_f32_e32 v2, 1.0, v2
	v_rcp_f32_e32 v11, v2
	v_and_b32_e32 v2, 0xffff0000, v128
	v_fma_f32 v3, v65, v2, v3
	v_mul_f32_e32 v2, 0x3d372713, v3
	v_mul_f32_e32 v2, v3, v2
	v_fma_f32 v2, v3, v2, v3
	v_mul_f32_e32 v2, 0x3fcc422a, v2
	v_mul_f32_e32 v2, 0xbfb8aa3b, v2
	v_exp_f32_e32 v2, v2
	v_lshl_add_u64 v[0:1], v[0:1], 0, s[94:95]
	v_lshl_add_u64 v[0:1], v[0:1], 0, v[120:121]
	v_add_f32_e32 v2, 1.0, v2
	v_rcp_f32_e32 v13, v2
	v_lshlrev_b32_e32 v2, 16, v129
	v_fma_f32 v15, v66, v2, v4
	v_mul_f32_e32 v2, 0x3d372713, v15
	v_mul_f32_e32 v2, v15, v2
	v_fma_f32 v2, v15, v2, v15
	v_mul_f32_e32 v2, 0x3fcc422a, v2
	v_mul_f32_e32 v2, 0xbfb8aa3b, v2
	v_exp_f32_e32 v2, v2
	s_nop 0
	v_add_f32_e32 v2, 1.0, v2
	v_rcp_f32_e32 v17, v2
	v_and_b32_e32 v2, 0xffff0000, v129
	v_fmac_f32_e32 v5, v67, v2
	v_mul_f32_e32 v2, 0x3d372713, v5
	v_mul_f32_e32 v2, v5, v2
	v_fma_f32 v2, v5, v2, v5
	v_mul_f32_e32 v2, 0x3fcc422a, v2
	v_mul_f32_e32 v2, 0xbfb8aa3b, v2
	v_exp_f32_e32 v2, v2
	s_nop 0
	v_add_f32_e32 v2, 1.0, v2
	v_rcp_f32_e32 v19, v2
	v_mul_f32_e32 v2, 0xbfb8aa3b, v10
	v_exp_f32_e32 v2, v2
	s_nop 0
	v_add_f32_e32 v2, 1.0, v2
	v_rcp_f32_e32 v8, v2
	v_mul_f32_e32 v2, 0xbfb8aa3b, v12
	v_exp_f32_e32 v2, v2
	v_pk_mul_f32 v[8:9], v[8:9], v[10:11]
	s_nop 0
	v_mul_f32_e32 v10, v8, v9
	v_add_f32_e32 v2, 1.0, v2
	v_rcp_f32_e32 v2, v2
	s_nop 0
	v_pk_mul_f32 v[2:3], v[2:3], v[12:13]
	s_nop 0
	v_mul_f32_e32 v11, v2, v3
	v_mul_f32_e32 v2, 0xbfb8aa3b, v16
	v_exp_f32_e32 v2, v2
	v_cvt_pk_bf16_f32 v8, v9, v3
	s_nop 0
	v_add_f32_e32 v2, 1.0, v2
	v_rcp_f32_e32 v14, v2
	s_nop 0
	v_pk_mul_f32 v[2:3], v[14:15], v[16:17]
	s_nop 0
	v_mul_f32_e32 v12, v2, v3
	v_mul_f32_e32 v2, 0xbfb8aa3b, v18
	v_exp_f32_e32 v2, v2
	v_lshlrev_b32_e32 v14, 16, v119
	v_and_b32_e32 v16, 0xffff0000, v119
	v_add_f32_e32 v2, 1.0, v2
	v_rcp_f32_e32 v4, v2
	v_add_co_u32_e32 v2, vcc, s92, v6
	v_pk_mul_f32 v[4:5], v[4:5], v[18:19]
	s_nop 0
	v_cvt_pk_bf16_f32 v9, v3, v5
	v_addc_co_u32_e32 v3, vcc, 0, v7, vcc
	global_store_dwordx2 v[2:3], v[8:9], off
	v_mul_f32_e32 v3, v4, v5
	v_cvt_pk_bf16_f32 v2, v10, v11
	v_cvt_pk_bf16_f32 v3, v12, v3
	global_store_dwordx2 v[6:7], v[2:3], off offset:2048
	ds_read_b128 v[2:5], v112 offset:4608
	ds_read_b128 v[6:9], v112 offset:4672
	s_waitcnt lgkmcnt(1)
	v_mfma_f32_16x16x32_bf16 v[2:5], v[80:83], v[2:5], 0
	v_and_b32_e32 v10, 0xffff0000, v118
	s_waitcnt lgkmcnt(0)
	v_mfma_f32_16x16x32_bf16 v[2:5], v[76:79], v[6:9], v[2:5]
	ds_read_b128 v[6:9], v112 offset:4736
	s_waitcnt lgkmcnt(0)
	v_mfma_f32_16x16x32_bf16 v[2:5], v[72:75], v[6:9], v[2:5]
	ds_read_b128 v[6:9], v112 offset:4800
	s_waitcnt lgkmcnt(0)
	v_mfma_f32_16x16x32_bf16 v[2:5], v[68:71], v[6:9], v[2:5]
	v_lshlrev_b32_e32 v6, 16, v122
	v_lshlrev_b32_e32 v8, 16, v118
	s_nop 5
	v_fma_f32 v7, v64, v6, v2
	v_mul_f32_e32 v2, 0x3d372713, v7
	v_mul_f32_e32 v2, v7, v2
	v_fma_f32 v2, v7, v2, v7
	v_mul_f32_e32 v2, 0x3fcc422a, v2
	v_mul_f32_e32 v2, 0xbfb8aa3b, v2
	v_exp_f32_e32 v2, v2
	s_nop 0
	v_add_f32_e32 v2, 1.0, v2
	v_rcp_f32_e32 v9, v2
	v_and_b32_e32 v2, 0xffff0000, v122
	v_fma_f32 v3, v65, v2, v3
	v_mul_f32_e32 v2, 0x3d372713, v3
	v_mul_f32_e32 v2, v3, v2
	v_fma_f32 v2, v3, v2, v3
	v_mul_f32_e32 v2, 0x3fcc422a, v2
	v_mul_f32_e32 v2, 0xbfb8aa3b, v2
	v_exp_f32_e32 v2, v2
	s_nop 0
	v_add_f32_e32 v2, 1.0, v2
	v_rcp_f32_e32 v11, v2
	v_lshlrev_b32_e32 v2, 16, v123
	v_fma_f32 v13, v66, v2, v4
	v_mul_f32_e32 v2, 0x3d372713, v13
	v_mul_f32_e32 v2, v13, v2
	v_fma_f32 v2, v13, v2, v13
	v_mul_f32_e32 v2, 0x3fcc422a, v2
	v_mul_f32_e32 v2, 0xbfb8aa3b, v2
	v_exp_f32_e32 v2, v2
	s_nop 0
	v_add_f32_e32 v2, 1.0, v2
	v_rcp_f32_e32 v15, v2
	v_and_b32_e32 v2, 0xffff0000, v123
	v_fmac_f32_e32 v5, v67, v2
	v_mul_f32_e32 v2, 0x3d372713, v5
	v_mul_f32_e32 v2, v5, v2
	v_fma_f32 v2, v5, v2, v5
	v_mul_f32_e32 v2, 0x3fcc422a, v2
	v_mul_f32_e32 v2, 0xbfb8aa3b, v2
	v_exp_f32_e32 v2, v2
	s_nop 0
	v_add_f32_e32 v2, 1.0, v2
	v_rcp_f32_e32 v17, v2
	v_mul_f32_e32 v2, 0xbfb8aa3b, v8
	v_exp_f32_e32 v2, v2
	s_nop 0
	v_add_f32_e32 v2, 1.0, v2
	v_rcp_f32_e32 v6, v2
	v_mul_f32_e32 v2, 0xbfb8aa3b, v10
	v_exp_f32_e32 v2, v2
	v_pk_mul_f32 v[6:7], v[6:7], v[8:9]
	s_nop 0
	v_mul_f32_e32 v8, v6, v7
	v_add_f32_e32 v2, 1.0, v2
	v_rcp_f32_e32 v2, v2
	s_nop 0
	v_pk_mul_f32 v[2:3], v[2:3], v[10:11]
	s_nop 0
	v_mul_f32_e32 v9, v2, v3
	v_mul_f32_e32 v2, 0xbfb8aa3b, v14
	v_exp_f32_e32 v2, v2
	v_cvt_pk_bf16_f32 v6, v7, v3
	s_nop 0
	v_add_f32_e32 v2, 1.0, v2
	v_rcp_f32_e32 v12, v2
	s_nop 0
	v_pk_mul_f32 v[2:3], v[12:13], v[14:15]
	s_nop 0
	v_mul_f32_e32 v10, v2, v3
	v_mul_f32_e32 v2, 0xbfb8aa3b, v16
	v_exp_f32_e32 v2, v2
	s_nop 0
	v_add_f32_e32 v2, 1.0, v2
	v_rcp_f32_e32 v4, v2
	v_add_co_u32_e32 v2, vcc, 0x2000, v0
	v_pk_mul_f32 v[4:5], v[4:5], v[16:17]
	s_nop 0
	v_cvt_pk_bf16_f32 v7, v3, v5
	v_addc_co_u32_e32 v3, vcc, 0, v1, vcc
	global_store_dwordx2 v[2:3], v[6:7], off
	v_mul_f32_e32 v3, v4, v5
	v_cvt_pk_bf16_f32 v2, v8, v9
	v_cvt_pk_bf16_f32 v3, v10, v3
	global_store_dwordx2 v[0:1], v[2:3], off offset:2048
	s_andn2_b64 vcc, exec, s[42:43]
	s_cbranch_vccnz .LBB0_741

.LBB0_768:
	v_and_b32_e32 v206, 3, v194
	v_lshlrev_b32_e32 v206, 2, v206
	v_and_b32_e32 v207, 12, v194
	v_lshl_or_b32 v206, v207, 3, v206
	v_and_b32_e32 v207, 32, v194
	v_lshl_or_b32 v206, v207, 2, v206
	v_add_u32_e32 v207, 16, v206
	v_and_b32_e32 v208, 16, v194
	s_ashr_i32 s22, s16, 6
	s_cmpk_lt_i32 s22, 0x80
	s_cselect_b64 s[44:45], -1, 0
	s_cmpk_gt_i32 s22, 0x7f
	s_cselect_b64 s[42:43], -1, 0
	v_mov_b32_e32 v6, v194
	s_mov_b64 s[0:1], -1
	s_and_b64 vcc, exec, s[42:43]
	s_cbranch_vccz .LBB0_770
	s_and_b32 s0, s16, 0xffffffc0
	s_add_i32 s23, s0, 0x2000
	s_add_i32 s24, s0, 0x2020
	s_mov_b64 s[0:1], 0

.LBB0_780:
	v_and_b32_e32 v0, 3, v6
	v_lshrrev_b32_e32 v1, 1, v6
	v_and_or_b32 v0, v1, 12, v0
	v_and_b32_e32 v1, 4, v6
	v_mov_b32_e32 v2, s24
	v_mov_b32_e32 v3, s23
	v_cmp_eq_u32_e32 vcc, 0, v1
	s_lshl_b32 s22, s25, 4
	v_and_b32_e32 v160, 15, v6
	v_cndmask_b32_e32 v1, v2, v3, vcc
	v_add_u32_e32 v2, v0, v1
	v_mov_b64_e32 v[0:1], s[86:87]
	v_mad_i64_i32 v[0:1], s[0:1], v2, s66, v[0:1]
	v_or_b32_e32 v2, s22, v160
	v_lshlrev_b32_e32 v2, 8, v2
	v_mov_b32_e32 v3, v173
	v_lshl_add_u64 v[2:3], s[34:35], 0, v[2:3]
	v_and_b32_e32 v34, 48, v6
	v_mov_b32_e32 v35, v173
	v_lshl_add_u64 v[2:3], v[2:3], 0, v[34:35]
	global_load_dword v157, v[4:5], off
	global_load_dwordx4 v[80:83], v[2:3], off
	global_load_dwordx4 v[76:79], v[2:3], off offset:64
	global_load_dwordx4 v[72:75], v[2:3], off offset:128
	global_load_dwordx4 v[68:71], v[2:3], off offset:192
	v_lshrrev_b32_e32 v2, 2, v6
	v_and_b32_e32 v4, 12, v2
	v_or_b32_e32 v2, s19, v4
	v_readlane_b32 s48, v237, 4
	v_or_b32_e32 v2, s22, v2
	v_mov_b32_e32 v3, v173
	v_readlane_b32 s54, v237, 10
	v_readlane_b32 s55, v237, 11
	v_lshlrev_b32_e32 v7, 3, v36
	s_lshl_b32 s94, s25, 5
	v_lshl_add_u64 v[2:3], v[2:3], 2, s[54:55]
	v_lshl_add_u64 v[0:1], v[0:1], 0, s[94:95]
	global_load_dwordx4 v[64:67], v[2:3], off
	v_lshlrev_b32_e32 v2, 1, v7
	v_mov_b32_e32 v3, v173
	s_add_u32 s0, s86, s94
	v_lshl_add_u64 v[2:3], v[0:1], 0, v[2:3]
	s_addc_u32 s1, s87, 0
	v_lshlrev_b32_e32 v120, 1, v4
	v_mov_b32_e32 v121, v173
	v_lshl_add_u64 v[0:1], s[0:1], 0, v[120:121]
	v_add_co_u32_e32 v4, vcc, s92, v2
	v_add_u32_e32 v16, s23, v160
	s_nop 0
	v_addc_co_u32_e32 v5, vcc, 0, v3, vcc
	v_mad_i64_i32 v[6:7], s[0:1], v16, s66, v[0:1]
	v_add_co_u32_e32 v8, vcc, s92, v6
	v_add_u32_e32 v17, s24, v160
	s_nop 0
	v_addc_co_u32_e32 v9, vcc, 0, v7, vcc
	global_load_dwordx4 v[48:51], v[4:5], off
	global_load_dwordx2 v[152:153], v[6:7], off offset:2048
	v_mad_i64_i32 v[4:5], s[0:1], v17, s66, v[0:1]
	v_add_co_u32_e32 v6, vcc, s92, v4
	s_mov_b32 s0, 0x32000
	s_nop 0
	v_addc_co_u32_e32 v7, vcc, 0, v5, vcc
	v_or_b32_e32 v10, 16, v160
	global_load_dwordx2 v[112:113], v[4:5], off offset:2048
	v_add_co_u32_e32 v4, vcc, s0, v2
	v_add_u32_e32 v18, s23, v10
	s_nop 0
	v_addc_co_u32_e32 v5, vcc, 0, v3, vcc
	v_mad_i64_i32 v[6:7], s[0:1], v18, s66, v[0:1]
	v_add_co_u32_e32 v8, vcc, s92, v6
	v_add_u32_e32 v33, s24, v10
	s_nop 0
	v_addc_co_u32_e32 v9, vcc, 0, v7, vcc
	global_load_dwordx4 v[108:111], v[4:5], off
	global_load_dwordx2 v[144:145], v[6:7], off offset:2048
	v_mad_i64_i32 v[4:5], s[0:1], v33, s66, v[0:1]
	v_add_co_u32_e32 v6, vcc, 0x2000, v4
	s_mov_b64 s[0:1], 0x2000
	s_nop 0
	v_addc_co_u32_e32 v7, vcc, 0, v5, vcc
	global_load_dwordx2 v[140:141], v[4:5], off offset:2048
	v_cndmask_b32_e64 v4, 0, 1, s[44:45]
	v_lshl_add_u64 v[2:3], v[2:3], 0, s[0:1]
	v_cmp_ne_u32_e64 s[0:1], 1, v4
	v_or_b32_e32 v4, 32, v160
	s_andn2_b64 vcc, exec, s[44:45]
	v_add_u32_e32 v165, s23, v4
	v_add_u32_e32 v164, s24, v4
	v_readlane_b32 s49, v237, 5
	v_readlane_b32 s50, v237, 6
	v_readlane_b32 s51, v237, 7
	v_readlane_b32 s52, v237, 8
	v_readlane_b32 s53, v237, 9
	v_readlane_b32 s56, v237, 12
	v_readlane_b32 s57, v237, 13
	v_readlane_b32 s58, v237, 14
	v_readlane_b32 s59, v237, 15
	v_readlane_b32 s60, v237, 16
	v_readlane_b32 s61, v237, 17
	v_readlane_b32 s62, v237, 18
	v_readlane_b32 s63, v237, 19
	s_cbranch_vccnz .LBB0_782
	v_add_co_u32_e32 v4, vcc, 0x60000, v2
	v_mad_i64_i32 v[6:7], s[26:27], v165, s66, v[0:1]
	s_nop 0
	v_addc_co_u32_e32 v5, vcc, 0, v3, vcc
	v_add_co_u32_e32 v8, vcc, 0x2000, v6
	global_load_dwordx4 v[104:107], v[4:5], off
	global_load_dwordx2 v[136:137], v[6:7], off offset:2048
	v_addc_co_u32_e32 v9, vcc, 0, v7, vcc
	v_mad_i64_i32 v[4:5], s[26:27], v164, s66, v[0:1]
	v_add_co_u32_e32 v6, vcc, 0x2000, v4
	s_nop 1
	v_addc_co_u32_e32 v7, vcc, 0, v5, vcc
	global_load_dwordx2 v[132:133], v[4:5], off offset:2048
.LBB0_782:
	v_or_b32_e32 v4, 48, v160
	s_and_b64 vcc, exec, s[0:1]
	v_add_u32_e32 v162, s23, v4
	v_add_u32_e32 v117, s24, v4
	s_movk_i32 s56, 0xc00
	s_cbranch_vccnz .LBB0_784
	v_add_co_u32_e32 v2, vcc, 0x90000, v2
	v_mad_i64_i32 v[4:5], s[24:25], v162, s66, v[0:1]
	s_nop 0
	v_addc_co_u32_e32 v3, vcc, 0, v3, vcc
	v_add_co_u32_e32 v6, vcc, 0x2000, v4
	v_mad_i64_i32 v[0:1], s[24:25], v117, s66, v[0:1]
	s_nop 0
	v_addc_co_u32_e32 v7, vcc, 0, v5, vcc
	global_load_dwordx4 v[100:103], v[2:3], off
	global_load_dwordx2 v[126:127], v[4:5], off offset:2048
	v_add_co_u32_e32 v2, vcc, 0x2000, v0
	s_nop 1
	v_addc_co_u32_e32 v3, vcc, 0, v1, vcc
	global_load_dwordx2 v[118:119], v[0:1], off offset:2048
.LBB0_784:
	s_waitcnt vmcnt(11)
	ds_bpermute_b32 v202, v206, v48
	ds_bpermute_b32 v203, v206, v49
	ds_bpermute_b32 v204, v206, v50
	ds_bpermute_b32 v205, v206, v51
	ds_bpermute_b32 v210, v207, v48
	ds_bpermute_b32 v211, v207, v49
	ds_bpermute_b32 v212, v207, v50
	ds_bpermute_b32 v213, v207, v51
	v_mfma_f32_32x32x16_bf16 v[0:15], v[48:51], v[84:87], 0
	v_mad_i64_i32 v[176:177], s[24:25], v16, s66, 0
	v_mad_i64_i32 v[178:179], s[24:25], v17, s66, 0
	v_mad_i64_i32 v[150:151], s[24:25], v18, s66, 0
	v_mov_b32_e32 v131, v53
	v_mfma_f32_32x32x16_bf16 v[16:31], v[48:51], v[88:91], 0
	v_lshlrev_b32_e32 v53, 2, v32
	v_mul_u32_u24_e32 v54, 0x1200, v36
	v_mov_b32_e32 v130, v125
	v_add3_u32 v163, s17, v53, v54
	v_mov_b32_e32 v125, v52
	s_nop 1
	v_mov_b32_e32 v52, v0
	v_mad_i64_i32 v[148:149], s[24:25], v33, s66, 0
	s_nop 2
	v_mov_b32_e32 v53, v16
	v_pk_fma_f32 v[52:53], v[124:125], v[114:115], v[52:53]
	v_add_u32_e32 v166, s17, v34
	v_mfma_f32_32x32x16_bf16 v[32:47], v[48:51], v[92:95], 0
	v_fma_f32 v174, -v130, v156, v52
	v_fma_f32 v175, -v131, v157, v53
	v_mov_b32_e32 v16, v1
	s_lshl_b32 s94, s22, 1
	v_mov_b32_e32 v121, v173
	s_movk_i32 s7, 0x120
	v_mul_u32_u24_e32 v167, 0x120, v160
	s_nop 4
	v_mov_b32_e32 v180, v32
	v_mfma_f32_32x32x16_bf16 v[48:63], v[48:51], v[96:99], 0
	s_waitcnt lgkmcnt(0)
	v_cmp_ne_u32_e64 s[26:27], 0, v208
	v_cndmask_b32_e64 v158, v202, v204, s[26:27]
	v_cndmask_b32_e64 v159, v203, v205, s[26:27]
	v_cndmask_b32_e64 v154, v210, v212, s[26:27]
	v_cndmask_b32_e64 v155, v211, v213, s[26:27]
	s_nop 11
	v_mov_b32_e32 v181, v48
	v_pk_fma_f32 v[156:157], v[124:125], v[156:157], v[180:181]
	v_mov_b32_e32 v48, v33
	v_pk_fma_f32 v[114:115], v[130:131], v[114:115], v[156:157]
	v_mov_b32_e32 v33, v18
	v_cvt_pk_bf16_f32 v0, v174, v114
	ds_write_b32 v163, v0
	v_cvt_pk_bf16_f32 v0, v175, v115
	ds_write_b32 v163, v0 offset:128
	v_pk_fma_f32 v[0:1], v[124:125], v[174:175], v[16:17]
	v_pk_fma_f32 v[16:17], v[124:125], v[114:115], v[48:49]
	v_pk_fma_f32 v[0:1], v[130:131], v[114:115], v[0:1] neg_lo:[1,0,0] neg_hi:[1,0,0]
	v_pk_fma_f32 v[16:17], v[130:131], v[174:175], v[16:17]
	v_mov_b32_e32 v48, v34
	v_cvt_pk_bf16_f32 v32, v0, v16
	ds_write_b32 v163, v32 offset:288
	v_cvt_pk_bf16_f32 v32, v1, v17
	ds_write_b32 v163, v32 offset:416
	v_mov_b32_e32 v32, v2
	v_pk_fma_f32 v[32:33], v[124:125], v[0:1], v[32:33]
	v_mov_b32_e32 v49, v50
	v_pk_fma_f32 v[32:33], v[130:131], v[16:17], v[32:33] neg_lo:[1,0,0] neg_hi:[1,0,0]
	v_pk_fma_f32 v[16:17], v[124:125], v[16:17], v[48:49]
	v_mov_b32_e32 v18, v3
	v_pk_fma_f32 v[0:1], v[130:131], v[0:1], v[16:17]
	v_mov_b32_e32 v50, v35
	v_cvt_pk_bf16_f32 v2, v32, v0
	ds_write_b32 v163, v2 offset:576
	v_cvt_pk_bf16_f32 v2, v33, v1
	ds_write_b32 v163, v2 offset:704
	v_pk_fma_f32 v[2:3], v[124:125], v[32:33], v[18:19]
	v_mov_b32_e32 v17, v20
	v_pk_fma_f32 v[2:3], v[130:131], v[0:1], v[2:3] neg_lo:[1,0,0] neg_hi:[1,0,0]
	v_pk_fma_f32 v[0:1], v[124:125], v[0:1], v[50:51]
	v_mov_b32_e32 v18, v36
	v_pk_fma_f32 v[0:1], v[130:131], v[32:33], v[0:1]
	v_mov_b32_e32 v19, v52
	v_cvt_pk_bf16_f32 v16, v2, v0
	ds_write_b32 v163, v16 offset:864
	v_cvt_pk_bf16_f32 v16, v3, v1
	ds_write_b32 v163, v16 offset:992
	v_mov_b32_e32 v16, v4
	v_pk_fma_f32 v[16:17], v[124:125], v[2:3], v[16:17]
	v_mov_b32_e32 v20, v5
	v_pk_fma_f32 v[16:17], v[130:131], v[0:1], v[16:17] neg_lo:[1,0,0] neg_hi:[1,0,0]
	v_pk_fma_f32 v[0:1], v[124:125], v[0:1], v[18:19]
	v_mov_b32_e32 v52, v37
	v_pk_fma_f32 v[0:1], v[130:131], v[2:3], v[0:1]
	v_mov_b32_e32 v5, v22
	v_cvt_pk_bf16_f32 v2, v16, v0
	ds_write_b32 v163, v2 offset:1152
	v_cvt_pk_bf16_f32 v2, v17, v1
	ds_write_b32 v163, v2 offset:1280
	v_pk_fma_f32 v[2:3], v[124:125], v[16:17], v[20:21]
	v_mov_b32_e32 v22, v7
	v_pk_fma_f32 v[2:3], v[130:131], v[0:1], v[2:3] neg_lo:[1,0,0] neg_hi:[1,0,0]
	v_pk_fma_f32 v[0:1], v[124:125], v[0:1], v[52:53]
	s_waitcnt vmcnt(10)
	v_lshlrev_b32_e32 v20, 16, v152
	v_pk_fma_f32 v[0:1], v[130:131], v[16:17], v[0:1]
	v_and_b32_e32 v18, 0xffff0000, v152
	v_cvt_pk_bf16_f32 v4, v2, v0
	ds_write_b32 v163, v4 offset:1440
	v_cvt_pk_bf16_f32 v4, v3, v1
	ds_write_b32 v163, v4 offset:1568
	v_mov_b32_e32 v4, v6
	v_pk_fma_f32 v[4:5], v[124:125], v[2:3], v[4:5]
	v_lshl_add_u64 v[48:49], s[86:87], 0, v[178:179]
	v_pk_fma_f32 v[34:35], v[130:131], v[0:1], v[4:5] neg_lo:[1,0,0] neg_hi:[1,0,0]
	v_mov_b32_e32 v4, v38
	v_mov_b32_e32 v5, v54
	v_pk_fma_f32 v[0:1], v[124:125], v[0:1], v[4:5]
	v_mul_f32_e32 v4, 0xbfb8aa3b, v18
	v_pk_fma_f32 v[0:1], v[130:131], v[2:3], v[0:1]
	v_exp_f32_e32 v4, v4
	v_cvt_pk_bf16_f32 v2, v34, v0
	ds_write_b32 v163, v2 offset:1728
	v_cvt_pk_bf16_f32 v2, v35, v1
	ds_write_b32 v163, v2 offset:1856
	v_pk_fma_f32 v[2:3], v[124:125], v[34:35], v[22:23]
	v_add_f32_e32 v6, 1.0, v4
	v_pk_fma_f32 v[36:37], v[130:131], v[0:1], v[2:3] neg_lo:[1,0,0] neg_hi:[1,0,0]
	v_mul_f32_e32 v2, 0xbfb8aa3b, v20
	v_exp_f32_e32 v2, v2
	v_lshlrev_b32_e32 v4, 16, v153
	v_lshl_add_u64 v[48:49], v[48:49], 0, s[94:95]
	v_rcp_f32_e32 v32, v6
	v_add_f32_e32 v2, 1.0, v2
	v_rcp_f32_e32 v22, v2
	v_mul_f32_e32 v2, 0xbfb8aa3b, v4
	v_exp_f32_e32 v16, v2
	v_and_b32_e32 v2, 0xffff0000, v153
	v_mul_f32_e32 v17, 0xbfb8aa3b, v2
	v_exp_f32_e32 v17, v17
	v_add_f32_e32 v6, 1.0, v16
	v_lshl_add_u64 v[152:153], v[48:49], 0, v[120:121]
	s_waitcnt vmcnt(9)
	v_lshlrev_b32_e32 v48, 16, v112
	v_rcp_f32_e32 v16, v6
	v_add_f32_e32 v6, 1.0, v17
	v_mul_f32_e32 v17, 0xbfb8aa3b, v48
	v_and_b32_e32 v50, 0xffff0000, v112
	v_exp_f32_e32 v17, v17
	v_mul_f32_e32 v21, 0xbfb8aa3b, v50
	v_exp_f32_e32 v21, v21
	v_mov_b32_e32 v54, v39
	v_pk_fma_f32 v[38:39], v[124:125], v[0:1], v[54:55]
	v_add_f32_e32 v17, 1.0, v17
	v_pk_fma_f32 v[34:35], v[130:131], v[34:35], v[38:39]
	v_mov_b32_e32 v38, v8
	v_mov_b32_e32 v39, v24
	v_rcp_f32_e32 v52, v17
	v_add_f32_e32 v17, 1.0, v21
	v_cvt_pk_bf16_f32 v21, v36, v34
	v_pk_fma_f32 v[38:39], v[124:125], v[36:37], v[38:39]
	v_mov_b32_e32 v54, v40
	v_mov_b32_e32 v55, v56
	ds_write_b32 v163, v21 offset:2016
	v_cvt_pk_bf16_f32 v21, v37, v35
	v_pk_fma_f32 v[38:39], v[130:131], v[34:35], v[38:39] neg_lo:[1,0,0] neg_hi:[1,0,0]
	v_pk_fma_f32 v[34:35], v[124:125], v[34:35], v[54:55]
	v_mov_b32_e32 v24, v9
	v_pk_fma_f32 v[34:35], v[130:131], v[36:37], v[34:35]
	v_mov_b32_e32 v56, v41
	v_cvt_pk_bf16_f32 v8, v38, v34
	ds_write_b32 v163, v8 offset:2304
	v_cvt_pk_bf16_f32 v8, v39, v35
	ds_write_b32 v163, v8 offset:2432
	v_pk_fma_f32 v[8:9], v[124:125], v[38:39], v[24:25]
	v_pk_fma_f32 v[24:25], v[124:125], v[34:35], v[56:57]
	v_pk_fma_f32 v[8:9], v[130:131], v[34:35], v[8:9] neg_lo:[1,0,0] neg_hi:[1,0,0]
	v_mov_b32_e32 v34, v10
	v_mov_b32_e32 v35, v26
	ds_write_b32 v163, v21 offset:2144
	v_pk_fma_f32 v[24:25], v[130:131], v[38:39], v[24:25]
	v_pk_fma_f32 v[34:35], v[124:125], v[8:9], v[34:35]
	v_cvt_pk_bf16_f32 v21, v8, v24
	v_mov_b32_e32 v36, v42
	v_mov_b32_e32 v37, v58
	ds_write_b32 v163, v21 offset:2592
	v_cvt_pk_bf16_f32 v21, v9, v25
	v_pk_fma_f32 v[34:35], v[130:131], v[24:25], v[34:35] neg_lo:[1,0,0] neg_hi:[1,0,0]
	v_pk_fma_f32 v[24:25], v[124:125], v[24:25], v[36:37]
	v_mov_b32_e32 v26, v11
	v_pk_fma_f32 v[8:9], v[130:131], v[8:9], v[24:25]
	v_mov_b32_e32 v58, v43
	v_cvt_pk_bf16_f32 v10, v34, v8
	ds_write_b32 v163, v10 offset:2880
	v_cvt_pk_bf16_f32 v10, v35, v9
	ds_write_b32 v163, v10 offset:3008
	v_pk_fma_f32 v[10:11], v[124:125], v[34:35], v[26:27]
	v_mov_b32_e32 v24, v12
	v_pk_fma_f32 v[10:11], v[130:131], v[8:9], v[10:11] neg_lo:[1,0,0] neg_hi:[1,0,0]
	v_pk_fma_f32 v[8:9], v[124:125], v[8:9], v[58:59]
	v_mov_b32_e32 v25, v28
	ds_write_b32 v163, v21 offset:2720
	v_pk_fma_f32 v[8:9], v[130:131], v[34:35], v[8:9]
	v_pk_fma_f32 v[24:25], v[124:125], v[10:11], v[24:25]
	v_cvt_pk_bf16_f32 v21, v10, v8
	v_mov_b32_e32 v26, v44
	v_mov_b32_e32 v27, v60
	ds_write_b32 v163, v21 offset:3168
	v_cvt_pk_bf16_f32 v21, v11, v9
	v_pk_fma_f32 v[24:25], v[130:131], v[8:9], v[24:25] neg_lo:[1,0,0] neg_hi:[1,0,0]
	v_pk_fma_f32 v[8:9], v[124:125], v[8:9], v[26:27]
	v_mov_b32_e32 v28, v13
	v_pk_fma_f32 v[8:9], v[130:131], v[10:11], v[8:9]
	v_mov_b32_e32 v60, v45
	v_cvt_pk_bf16_f32 v10, v24, v8
	ds_write_b32 v163, v10 offset:3456
	v_cvt_pk_bf16_f32 v10, v25, v9
	ds_write_b32 v163, v10 offset:3584
	v_pk_fma_f32 v[10:11], v[124:125], v[24:25], v[28:29]
	v_mov_b32_e32 v13, v30
	v_pk_fma_f32 v[10:11], v[130:131], v[8:9], v[10:11] neg_lo:[1,0,0] neg_hi:[1,0,0]
	v_pk_fma_f32 v[8:9], v[124:125], v[8:9], v[60:61]
	v_mov_b32_e32 v30, v15
	v_pk_fma_f32 v[8:9], v[130:131], v[24:25], v[8:9]
	v_mov_b32_e32 v24, v46
	v_cvt_pk_bf16_f32 v12, v10, v8
	ds_write_b32 v163, v12 offset:3744
	v_cvt_pk_bf16_f32 v12, v11, v9
	ds_write_b32 v163, v12 offset:3872
	v_mov_b32_e32 v12, v14
	v_pk_fma_f32 v[12:13], v[124:125], v[10:11], v[12:13]
	v_mov_b32_e32 v25, v62
	v_pk_fma_f32 v[12:13], v[130:131], v[8:9], v[12:13] neg_lo:[1,0,0] neg_hi:[1,0,0]
	v_pk_fma_f32 v[8:9], v[124:125], v[8:9], v[24:25]
	v_mov_b32_e32 v62, v47
	v_pk_fma_f32 v[8:9], v[130:131], v[10:11], v[8:9]
	v_mad_u32_u24 v174, v160, s7, v166
	v_cvt_pk_bf16_f32 v10, v12, v8
	ds_write_b32 v163, v10 offset:4032
	v_cvt_pk_bf16_f32 v10, v13, v9
	ds_write_b32 v163, v10 offset:4160
	v_pk_fma_f32 v[10:11], v[124:125], v[12:13], v[30:31]
	v_lshl_add_u64 v[0:1], s[86:87], 0, v[176:177]
	v_pk_fma_f32 v[160:161], v[130:131], v[8:9], v[10:11] neg_lo:[1,0,0] neg_hi:[1,0,0]
	v_pk_fma_f32 v[8:9], v[124:125], v[8:9], v[62:63]
	ds_write_b32 v163, v21 offset:3296
	v_pk_fma_f32 v[176:177], v[130:131], v[12:13], v[8:9]
	v_lshlrev_b32_e32 v49, 16, v154
	v_cvt_pk_bf16_f32 v8, v160, v176
	ds_write_b32 v163, v8 offset:4320
	v_cvt_pk_bf16_f32 v8, v161, v177
	ds_write_b32 v163, v8 offset:4448
	ds_read_b128 v[8:11], v174
	ds_read_b128 v[12:15], v174 offset:64
	s_waitcnt lgkmcnt(1)
	v_mfma_f32_16x16x32_bf16 v[8:11], v[80:83], v[8:11], 0
	ds_read_b128 v[24:27], v174 offset:128
	v_and_b32_e32 v51, 0xffff0000, v154
	v_and_b32_e32 v154, 0xffff0000, v113
	s_waitcnt lgkmcnt(1)
	v_mfma_f32_16x16x32_bf16 v[8:11], v[76:79], v[12:15], v[8:11]
	v_mul_f32_e32 v12, 0xbfb8aa3b, v154
	v_exp_f32_e32 v21, v12
	ds_read_b128 v[12:15], v174 offset:192
	s_waitcnt lgkmcnt(1)
	v_mfma_f32_16x16x32_bf16 v[8:11], v[72:75], v[24:27], v[8:11]
	v_lshlrev_b32_e32 v3, 16, v158
	v_and_b32_e32 v5, 0xffff0000, v158
	v_lshlrev_b32_e32 v56, 16, v113
	s_waitcnt lgkmcnt(0)
	v_mfma_f32_16x16x32_bf16 v[8:11], v[68:71], v[12:15], v[8:11]
	v_rcp_f32_e32 v54, v17
	v_mul_f32_e32 v17, 0xbfb8aa3b, v56
	v_exp_f32_e32 v17, v17
	v_lshlrev_b32_e32 v7, 16, v159
	v_and_b32_e32 v19, 0xffff0000, v159
	s_nop 2
	v_fma_f32 v23, v64, v3, v8
	v_mul_f32_e32 v3, 0x3d372713, v23
	v_fma_f32 v33, v65, v5, v9
	v_mul_f32_e32 v3, v23, v3
	v_mul_f32_e32 v5, 0x3d372713, v33
	v_fma_f32 v3, v23, v3, v23
	v_mul_f32_e32 v5, v33, v5
	v_mul_f32_e32 v3, 0x3fcc422a, v3
	v_fma_f32 v5, v33, v5, v33
	v_mul_f32_e32 v3, 0xbfb8aa3b, v3
	v_mul_f32_e32 v5, 0x3fcc422a, v5
	v_exp_f32_e32 v3, v3
	v_mul_f32_e32 v5, 0xbfb8aa3b, v5
	v_exp_f32_e32 v5, v5
	v_add_f32_e32 v17, 1.0, v17
	v_rcp_f32_e32 v58, v17
	v_add_f32_e32 v17, 1.0, v21
	v_rcp_f32_e32 v156, v17
	v_add_f32_e32 v3, 1.0, v3
	v_fma_f32 v17, v66, v7, v10
	v_rcp_f32_e32 v21, v3
	v_add_f32_e32 v3, 1.0, v5
	v_mul_f32_e32 v5, 0x3d372713, v17
	v_mul_f32_e32 v5, v17, v5
	v_fma_f32 v5, v17, v5, v17
	v_mul_f32_e32 v5, 0x3fcc422a, v5
	v_fmac_f32_e32 v11, v67, v19
	v_mul_f32_e32 v5, 0xbfb8aa3b, v5
	v_mul_f32_e32 v7, 0x3d372713, v11
	v_exp_f32_e32 v5, v5
	v_mul_f32_e32 v7, v11, v7
	v_fma_f32 v7, v11, v7, v11
	v_mul_f32_e32 v7, 0x3fcc422a, v7
	v_mul_f32_e32 v7, 0xbfb8aa3b, v7
	v_exp_f32_e32 v7, v7
	v_rcp_f32_e32 v19, v3
	v_add_f32_e32 v3, 1.0, v5
	v_rcp_f32_e32 v5, v3
	ds_read_b128 v[12:15], v174 offset:4608
	v_add_f32_e32 v3, 1.0, v7
	v_pk_mul_f32 v[18:19], v[32:33], v[18:19]
	v_rcp_f32_e32 v6, v6
	v_rcp_f32_e32 v3, v3
	v_pk_mul_f32 v[8:9], v[22:23], v[20:21]
	v_mul_f32_e32 v23, v18, v19
	v_cvt_pk_bf16_f32 v10, v9, v19
	v_pk_mul_f32 v[4:5], v[16:17], v[4:5]
	ds_read_b128 v[16:19], v174 offset:4672
	s_waitcnt lgkmcnt(1)
	v_mfma_f32_16x16x32_bf16 v[12:15], v[80:83], v[12:15], 0
	v_mov_b32_e32 v7, v11
	v_lshl_add_u64 v[0:1], v[0:1], 0, s[94:95]
	v_mul_f32_e32 v22, v8, v9
	v_pk_mul_f32 v[20:21], v[6:7], v[2:3]
	ds_read_b128 v[6:9], v174 offset:4736
	v_lshl_add_u64 v[0:1], v[0:1], 0, v[120:121]
	v_mul_f32_e32 v24, v4, v5
	v_cvt_pk_bf16_f32 v11, v5, v21
	s_waitcnt lgkmcnt(1)
	v_mfma_f32_16x16x32_bf16 v[2:5], v[76:79], v[16:19], v[12:15]
	v_lshlrev_b32_e32 v157, 16, v155
	v_and_b32_e32 v155, 0xffff0000, v155
	s_nop 0
	v_add_co_u32_e32 v12, vcc, s92, v0
	s_nop 1
	v_addc_co_u32_e32 v13, vcc, 0, v1, vcc
	global_store_dwordx2 v[12:13], v[10:11], off
	ds_read_b128 v[10:13], v174 offset:4800
	s_waitcnt lgkmcnt(1)
	v_mfma_f32_16x16x32_bf16 v[2:5], v[72:75], v[6:9], v[2:5]
	v_mul_f32_e32 v7, v20, v21
	v_cvt_pk_bf16_f32 v6, v22, v23
	v_cvt_pk_bf16_f32 v7, v24, v7
	s_waitcnt lgkmcnt(0)
	v_mfma_f32_16x16x32_bf16 v[112:115], v[68:71], v[10:13], v[2:5]
	global_store_dwordx2 v[0:1], v[6:7], off offset:2048
	s_nop 6
	v_fma_f32 v53, v64, v49, v112
	v_mul_f32_e32 v2, 0x3d372713, v53
	v_mul_f32_e32 v2, v53, v2
	v_fma_f32 v2, v53, v2, v53
	v_mul_f32_e32 v2, 0x3fcc422a, v2
	v_mul_f32_e32 v2, 0xbfb8aa3b, v2
	v_exp_f32_e32 v2, v2
	v_fma_f32 v55, v65, v51, v113
	v_fma_f32 v59, v66, v157, v114
	v_mul_f32_e32 v3, 0x3d372713, v55
	v_add_f32_e32 v0, 1.0, v2
	v_rcp_f32_e32 v49, v0
	v_mul_f32_e32 v0, 0x3d372713, v59
	v_mul_f32_e32 v3, v55, v3
	v_mul_f32_e32 v0, v59, v0
	v_fma_f32 v3, v55, v3, v55
	v_fma_f32 v0, v59, v0, v59
	v_mul_f32_e32 v3, 0x3fcc422a, v3
	v_mul_f32_e32 v16, 0x3fcc422a, v0
	v_mul_f32_e32 v3, 0xbfb8aa3b, v3
	v_mul_f32_e32 v16, 0xbfb8aa3b, v16
	v_fmac_f32_e32 v115, v67, v155
	v_exp_f32_e32 v3, v3
	v_exp_f32_e32 v33, v16
	v_mul_f32_e32 v16, 0x3d372713, v115
	v_mul_f32_e32 v16, v115, v16
	v_fma_f32 v16, v115, v16, v115
	v_mul_f32_e32 v34, 0x3fcc422a, v16
	v_add_f32_e32 v32, 1.0, v3
	v_mul_f32_e32 v34, 0xbfb8aa3b, v34
	v_exp_f32_e32 v34, v34
	v_rcp_f32_e32 v51, v32
	v_add_f32_e32 v32, 1.0, v33
	v_rcp_f32_e32 v57, v32
	v_add_f32_e32 v32, 1.0, v34
	v_pk_mul_f32 v[48:49], v[52:53], v[48:49]
	v_pk_mul_f32 v[50:51], v[54:55], v[50:51]
	s_waitcnt vmcnt(10)
	ds_bpermute_b32 v202, v206, v108
	ds_bpermute_b32 v203, v206, v109
	ds_bpermute_b32 v204, v206, v110
	ds_bpermute_b32 v205, v206, v111
	ds_bpermute_b32 v210, v207, v108
	ds_bpermute_b32 v211, v207, v109
	ds_bpermute_b32 v212, v207, v110
	ds_bpermute_b32 v213, v207, v111
	v_mfma_f32_32x32x16_bf16 v[0:15], v[108:111], v[84:87], 0
	v_rcp_f32_e32 v155, v32
	v_mul_f32_e32 v114, v48, v49
	v_cvt_pk_bf16_f32 v112, v49, v51
	v_mul_f32_e32 v175, v50, v51
	v_pk_mul_f32 v[158:159], v[58:59], v[56:57]
	v_mov_b32_e32 v157, v115
	v_mul_f32_e32 v158, v158, v159
	v_mfma_f32_32x32x16_bf16 v[16:31], v[108:111], v[88:91], 0
	v_add_u32_e32 v115, 0xc00, v163
	v_mfma_f32_32x32x16_bf16 v[32:47], v[108:111], v[92:95], 0
	v_mfma_f32_32x32x16_bf16 v[48:63], v[108:111], v[96:99], 0
	s_waitcnt lgkmcnt(0)
	v_cmp_ne_u32_e64 s[26:27], 0, v208
	v_cndmask_b32_e64 v146, v202, v204, s[26:27]
	v_cndmask_b32_e64 v147, v203, v205, s[26:27]
	v_cndmask_b32_e64 v142, v210, v212, s[26:27]
	v_cndmask_b32_e64 v143, v211, v213, s[26:27]
	s_nop 1
	v_mov_b32_e32 v108, v0
	s_nop 5
	v_mov_b32_e32 v109, v16
	s_nop 0
	v_mov_b32_e32 v110, v32
	v_fma_f32 v108, v124, v160, v108
	v_fma_f32 v109, v125, v161, v109
	v_mov_b32_e32 v16, v1
	v_pk_fma_f32 v[108:109], v[130:131], v[176:177], v[108:109] neg_lo:[1,0,0] neg_hi:[1,0,0]
	v_mov_b32_e32 v111, v48
	v_pk_fma_f32 v[110:111], v[124:125], v[176:177], v[110:111]
	v_mov_b32_e32 v48, v33
	v_pk_fma_f32 v[110:111], v[130:131], v[160:161], v[110:111]
	v_mov_b32_e32 v33, v18
	v_cvt_pk_bf16_f32 v0, v108, v110
	ds_write_b32 v163, v0
	v_cvt_pk_bf16_f32 v0, v109, v111
	ds_write_b32 v163, v0 offset:128
	v_pk_fma_f32 v[0:1], v[124:125], v[108:109], v[16:17]
	v_pk_fma_f32 v[16:17], v[124:125], v[110:111], v[48:49]
	v_pk_fma_f32 v[0:1], v[130:131], v[110:111], v[0:1] neg_lo:[1,0,0] neg_hi:[1,0,0]
	v_pk_fma_f32 v[16:17], v[130:131], v[108:109], v[16:17]
	v_mov_b32_e32 v48, v34
	v_cvt_pk_bf16_f32 v32, v0, v16
	ds_write_b32 v163, v32 offset:288
	v_cvt_pk_bf16_f32 v32, v1, v17
	ds_write_b32 v163, v32 offset:416
	v_mov_b32_e32 v32, v2
	v_pk_fma_f32 v[32:33], v[124:125], v[0:1], v[32:33]
	v_mov_b32_e32 v49, v50
	v_pk_fma_f32 v[32:33], v[130:131], v[16:17], v[32:33] neg_lo:[1,0,0] neg_hi:[1,0,0]
	v_pk_fma_f32 v[16:17], v[124:125], v[16:17], v[48:49]
	v_mov_b32_e32 v18, v3
	v_pk_fma_f32 v[0:1], v[130:131], v[0:1], v[16:17]
	v_mov_b32_e32 v50, v35
	v_cvt_pk_bf16_f32 v2, v32, v0
	ds_write_b32 v163, v2 offset:576
	v_cvt_pk_bf16_f32 v2, v33, v1
	ds_write_b32 v163, v2 offset:704
	v_pk_fma_f32 v[2:3], v[124:125], v[32:33], v[18:19]
	v_mov_b32_e32 v17, v20
	v_pk_fma_f32 v[2:3], v[130:131], v[0:1], v[2:3] neg_lo:[1,0,0] neg_hi:[1,0,0]
	v_pk_fma_f32 v[0:1], v[124:125], v[0:1], v[50:51]
	v_mov_b32_e32 v18, v36
	v_pk_fma_f32 v[0:1], v[130:131], v[32:33], v[0:1]
	v_mov_b32_e32 v19, v52
	v_cvt_pk_bf16_f32 v16, v2, v0
	ds_write_b32 v163, v16 offset:864
	v_cvt_pk_bf16_f32 v16, v3, v1
	ds_write_b32 v163, v16 offset:992
	v_mov_b32_e32 v16, v4
	v_pk_fma_f32 v[16:17], v[124:125], v[2:3], v[16:17]
	v_mov_b32_e32 v20, v5
	v_pk_fma_f32 v[16:17], v[130:131], v[0:1], v[16:17] neg_lo:[1,0,0] neg_hi:[1,0,0]
	v_pk_fma_f32 v[0:1], v[124:125], v[0:1], v[18:19]
	v_mov_b32_e32 v52, v37
	v_pk_fma_f32 v[0:1], v[130:131], v[2:3], v[0:1]
	v_mov_b32_e32 v5, v22
	v_cvt_pk_bf16_f32 v2, v16, v0
	ds_write_b32 v163, v2 offset:1152
	v_cvt_pk_bf16_f32 v2, v17, v1
	ds_write_b32 v163, v2 offset:1280
	v_pk_fma_f32 v[2:3], v[124:125], v[16:17], v[20:21]
	v_mov_b32_e32 v22, v7
	v_pk_fma_f32 v[2:3], v[130:131], v[0:1], v[2:3] neg_lo:[1,0,0] neg_hi:[1,0,0]
	v_pk_fma_f32 v[0:1], v[124:125], v[0:1], v[52:53]
	v_mov_b32_e32 v7, v56
	v_pk_fma_f32 v[0:1], v[130:131], v[16:17], v[0:1]
	v_mov_b32_e32 v16, v38
	v_cvt_pk_bf16_f32 v4, v2, v0
	ds_write_b32 v163, v4 offset:1440
	v_cvt_pk_bf16_f32 v4, v3, v1
	ds_write_b32 v163, v4 offset:1568
	v_mov_b32_e32 v4, v6
	v_pk_fma_f32 v[4:5], v[124:125], v[2:3], v[4:5]
	v_mov_b32_e32 v17, v54
	v_pk_fma_f32 v[4:5], v[130:131], v[0:1], v[4:5] neg_lo:[1,0,0] neg_hi:[1,0,0]
	v_pk_fma_f32 v[0:1], v[124:125], v[0:1], v[16:17]
	v_mov_b32_e32 v54, v39
	v_pk_fma_f32 v[0:1], v[130:131], v[2:3], v[0:1]
	v_mov_b32_e32 v6, v40
	v_cvt_pk_bf16_f32 v2, v4, v0
	ds_write_b32 v163, v2 offset:1728
	v_cvt_pk_bf16_f32 v2, v5, v1
	ds_write_b32 v163, v2 offset:1856
	v_pk_fma_f32 v[2:3], v[124:125], v[4:5], v[22:23]
	v_mov_b32_e32 v56, v41
	v_pk_fma_f32 v[2:3], v[130:131], v[0:1], v[2:3] neg_lo:[1,0,0] neg_hi:[1,0,0]
	v_pk_fma_f32 v[0:1], v[124:125], v[0:1], v[54:55]
	s_waitcnt vmcnt(9)
	v_and_b32_e32 v16, 0xffff0000, v145
	v_pk_fma_f32 v[0:1], v[130:131], v[4:5], v[0:1]
	v_mov_b32_e32 v5, v24
	v_cvt_pk_bf16_f32 v4, v2, v0
	ds_write_b32 v163, v4 offset:2016
	v_cvt_pk_bf16_f32 v4, v3, v1
	ds_write_b32 v163, v4 offset:2144
	v_mov_b32_e32 v4, v8
	v_pk_fma_f32 v[4:5], v[124:125], v[2:3], v[4:5]
	v_mov_b32_e32 v24, v9
	v_pk_fma_f32 v[4:5], v[130:131], v[0:1], v[4:5] neg_lo:[1,0,0] neg_hi:[1,0,0]
	v_pk_fma_f32 v[0:1], v[124:125], v[0:1], v[6:7]
	v_mov_b32_e32 v6, v42
	v_pk_fma_f32 v[0:1], v[130:131], v[2:3], v[0:1]
	v_mov_b32_e32 v7, v58
	v_cvt_pk_bf16_f32 v2, v4, v0
	ds_write_b32 v163, v2 offset:2304
	v_cvt_pk_bf16_f32 v2, v5, v1
	ds_write_b32 v163, v2 offset:2432
	v_pk_fma_f32 v[2:3], v[124:125], v[4:5], v[24:25]
	v_mov_b32_e32 v58, v43
	v_pk_fma_f32 v[2:3], v[130:131], v[0:1], v[2:3] neg_lo:[1,0,0] neg_hi:[1,0,0]
	v_pk_fma_f32 v[0:1], v[124:125], v[0:1], v[56:57]
	s_nop 0
	v_pk_fma_f32 v[0:1], v[130:131], v[4:5], v[0:1]
	v_mov_b32_e32 v5, v26
	v_cvt_pk_bf16_f32 v4, v2, v0
	ds_write_b32 v163, v4 offset:2592
	v_cvt_pk_bf16_f32 v4, v3, v1
	ds_write_b32 v163, v4 offset:2720
	v_mov_b32_e32 v4, v10
	v_pk_fma_f32 v[4:5], v[124:125], v[2:3], v[4:5]
	v_mov_b32_e32 v26, v11
	v_pk_fma_f32 v[4:5], v[130:131], v[0:1], v[4:5] neg_lo:[1,0,0] neg_hi:[1,0,0]
	v_pk_fma_f32 v[0:1], v[124:125], v[0:1], v[6:7]
	v_mov_b32_e32 v6, v44
	v_pk_fma_f32 v[0:1], v[130:131], v[2:3], v[0:1]
	v_mov_b32_e32 v7, v60
	v_cvt_pk_bf16_f32 v2, v4, v0
	ds_write_b32 v163, v2 offset:2880
	v_cvt_pk_bf16_f32 v2, v5, v1
	ds_write_b32 v163, v2 offset:3008
	v_pk_fma_f32 v[2:3], v[124:125], v[4:5], v[26:27]
	v_mov_b32_e32 v60, v45
	v_pk_fma_f32 v[2:3], v[130:131], v[0:1], v[2:3] neg_lo:[1,0,0] neg_hi:[1,0,0]
	v_pk_fma_f32 v[0:1], v[124:125], v[0:1], v[58:59]
	s_nop 0
	v_pk_fma_f32 v[0:1], v[130:131], v[4:5], v[0:1]
	v_mov_b32_e32 v5, v28
	v_cvt_pk_bf16_f32 v4, v2, v0
	ds_write_b32 v163, v4 offset:3168
	v_cvt_pk_bf16_f32 v4, v3, v1
	ds_write_b32 v163, v4 offset:3296
	v_mov_b32_e32 v4, v12
	v_pk_fma_f32 v[4:5], v[124:125], v[2:3], v[4:5]
	v_mov_b32_e32 v28, v13
	v_pk_fma_f32 v[4:5], v[130:131], v[0:1], v[4:5] neg_lo:[1,0,0] neg_hi:[1,0,0]
	v_pk_fma_f32 v[0:1], v[124:125], v[0:1], v[6:7]
	v_mov_b32_e32 v6, v46
	v_pk_fma_f32 v[0:1], v[130:131], v[2:3], v[0:1]
	v_mov_b32_e32 v7, v62
	v_cvt_pk_bf16_f32 v2, v4, v0
	ds_write_b32 v163, v2 offset:3456
	v_cvt_pk_bf16_f32 v2, v5, v1
	ds_write_b32 v163, v2 offset:3584
	v_pk_fma_f32 v[2:3], v[124:125], v[4:5], v[28:29]
	v_mov_b32_e32 v62, v47
	v_pk_fma_f32 v[2:3], v[130:131], v[0:1], v[2:3] neg_lo:[1,0,0] neg_hi:[1,0,0]
	v_pk_fma_f32 v[0:1], v[124:125], v[0:1], v[60:61]
	v_pk_mul_f32 v[12:13], v[156:157], v[154:155]
	v_pk_fma_f32 v[0:1], v[130:131], v[4:5], v[0:1]
	v_mov_b32_e32 v5, v30
	v_cvt_pk_bf16_f32 v4, v2, v0
	ds_write_b32 v163, v4 offset:3744
	v_cvt_pk_bf16_f32 v4, v3, v1
	ds_write_b32 v163, v4 offset:3872
	v_mov_b32_e32 v4, v14
	v_pk_fma_f32 v[4:5], v[124:125], v[2:3], v[4:5]
	v_mov_b32_e32 v30, v15
	v_pk_fma_f32 v[4:5], v[130:131], v[0:1], v[4:5] neg_lo:[1,0,0] neg_hi:[1,0,0]
	v_pk_fma_f32 v[0:1], v[124:125], v[0:1], v[6:7]
	v_cvt_pk_bf16_f32 v113, v159, v13
	v_add_co_u32_e32 v14, vcc, s92, v152
	v_pk_fma_f32 v[0:1], v[130:131], v[2:3], v[0:1]
	s_nop 0
	v_addc_co_u32_e32 v15, vcc, 0, v153, vcc
	v_cvt_pk_bf16_f32 v2, v4, v0
	ds_write_b32 v163, v2 offset:4032
	v_cvt_pk_bf16_f32 v2, v5, v1
	ds_write_b32 v163, v2 offset:4160
	v_pk_fma_f32 v[2:3], v[124:125], v[4:5], v[30:31]
	global_store_dwordx2 v[14:15], v[112:113], off
	v_pk_fma_f32 v[108:109], v[130:131], v[0:1], v[2:3] neg_lo:[1,0,0] neg_hi:[1,0,0]
	v_pk_fma_f32 v[0:1], v[124:125], v[0:1], v[62:63]
	v_cvt_pk_bf16_f32 v14, v114, v175
	v_add_u32_e32 v112, v166, v167
	v_pk_fma_f32 v[110:111], v[130:131], v[4:5], v[0:1]
	v_add_u32_e32 v114, 0xe00, v163
	v_cvt_pk_bf16_f32 v0, v108, v110
	ds_write_b32 v163, v0 offset:4320
	v_cvt_pk_bf16_f32 v0, v109, v111
	ds_write_b32 v163, v0 offset:4448
	ds_read_b128 v[0:3], v174
	ds_read_b128 v[4:7], v174 offset:64
	s_waitcnt lgkmcnt(1)
	v_mfma_f32_16x16x32_bf16 v[0:3], v[80:83], v[0:3], 0
	ds_read_b128 v[8:11], v174 offset:128
	v_add_u32_e32 v113, 0x1000, v163
	s_waitcnt lgkmcnt(1)
	v_mfma_f32_16x16x32_bf16 v[0:3], v[76:79], v[4:7], v[0:3]
	ds_read_b128 v[4:7], v174 offset:192
	s_waitcnt lgkmcnt(1)
	v_mfma_f32_16x16x32_bf16 v[0:3], v[72:75], v[8:11], v[0:3]
	v_mul_f32_e32 v8, v12, v13
	v_cvt_pk_bf16_f32 v15, v158, v8
	global_store_dwordx2 v[152:153], v[14:15], off offset:2048
	s_waitcnt lgkmcnt(0)
	v_mfma_f32_16x16x32_bf16 v[0:3], v[68:71], v[4:7], v[0:3]
	v_lshlrev_b32_e32 v4, 16, v146
	v_lshl_add_u64 v[6:7], s[86:87], 0, v[150:151]
	v_lshl_add_u64 v[6:7], v[6:7], 0, s[94:95]
	v_lshl_add_u64 v[12:13], v[6:7], 0, v[120:121]
	v_lshlrev_b32_e32 v6, 16, v147
	s_nop 1
	v_fma_f32 v5, v64, v4, v0
	v_and_b32_e32 v4, 0xffff0000, v146
	v_mul_f32_e32 v0, 0x3d372713, v5
	v_fma_f32 v1, v65, v4, v1
	v_mul_f32_e32 v0, v5, v0
	v_mul_f32_e32 v4, 0x3d372713, v1
	v_fma_f32 v7, v66, v6, v2
	v_fma_f32 v0, v5, v0, v5
	v_mul_f32_e32 v4, v1, v4
	v_mul_f32_e32 v2, 0x3d372713, v7
	v_mul_f32_e32 v0, 0x3fcc422a, v0
	v_fma_f32 v4, v1, v4, v1
	v_mul_f32_e32 v2, v7, v2
	v_mul_f32_e32 v0, 0xbfb8aa3b, v0
	v_mul_f32_e32 v4, 0x3fcc422a, v4
	v_fma_f32 v2, v7, v2, v7
	v_exp_f32_e32 v0, v0
	v_mul_f32_e32 v4, 0xbfb8aa3b, v4
	v_mul_f32_e32 v2, 0x3fcc422a, v2
	v_exp_f32_e32 v4, v4
	v_mul_f32_e32 v2, 0xbfb8aa3b, v2
	v_exp_f32_e32 v2, v2
	v_add_f32_e32 v0, 1.0, v0
	v_rcp_f32_e32 v9, v0
	v_add_f32_e32 v0, 1.0, v4
	v_rcp_f32_e32 v11, v0
	v_add_f32_e32 v0, 1.0, v2
	v_rcp_f32_e32 v15, v0
	v_and_b32_e32 v0, 0xffff0000, v147
	v_fmac_f32_e32 v3, v67, v0
	v_mul_f32_e32 v0, 0x3d372713, v3
	v_mul_f32_e32 v0, v3, v0
	v_fma_f32 v0, v3, v0, v3
	v_mul_f32_e32 v0, 0x3fcc422a, v0
	v_lshlrev_b32_e32 v8, 16, v144
	v_mul_f32_e32 v0, 0xbfb8aa3b, v0
	v_mul_f32_e32 v2, 0xbfb8aa3b, v8
	v_exp_f32_e32 v0, v0
	v_exp_f32_e32 v2, v2
	v_and_b32_e32 v10, 0xffff0000, v144
	v_mul_f32_e32 v4, 0xbfb8aa3b, v10
	v_add_f32_e32 v14, 1.0, v0
	v_add_f32_e32 v0, 1.0, v2
	v_exp_f32_e32 v6, v4
	v_rcp_f32_e32 v4, v0
	v_rcp_f32_e32 v17, v14
	v_lshlrev_b32_e32 v14, 16, v145
	v_mul_f32_e32 v2, 0xbfb8aa3b, v14
	v_exp_f32_e32 v2, v2
	v_add_f32_e32 v0, 1.0, v6
	v_pk_mul_f32 v[4:5], v[4:5], v[8:9]
	v_rcp_f32_e32 v0, v0
	v_mul_f32_e32 v20, v4, v5
	v_mul_f32_e32 v4, 0xbfb8aa3b, v16
	v_exp_f32_e32 v4, v4
	v_add_f32_e32 v2, 1.0, v2
	v_rcp_f32_e32 v6, v2
	v_pk_mul_f32 v[0:1], v[0:1], v[10:11]
	ds_read_b128 v[8:11], v174 offset:4736
	v_mul_f32_e32 v21, v0, v1
	v_add_f32_e32 v0, 1.0, v4
	v_cvt_pk_bf16_f32 v18, v5, v1
	v_rcp_f32_e32 v2, v0
	v_pk_mul_f32 v[0:1], v[6:7], v[14:15]
	ds_read_b128 v[4:7], v174 offset:4608
	v_mul_f32_e32 v22, v0, v1
	v_pk_mul_f32 v[14:15], v[2:3], v[16:17]
	v_add_co_u32_e32 v16, vcc, s92, v12
	v_cvt_pk_bf16_f32 v19, v1, v15
	ds_read_b128 v[0:3], v174 offset:4672
	s_waitcnt lgkmcnt(1)
	v_mfma_f32_16x16x32_bf16 v[4:7], v[80:83], v[4:7], 0
	v_addc_co_u32_e32 v17, vcc, 0, v13, vcc
	global_store_dwordx2 v[16:17], v[18:19], off
	s_waitcnt lgkmcnt(0)
	v_mfma_f32_16x16x32_bf16 v[0:3], v[76:79], v[0:3], v[4:7]
	v_cvt_pk_bf16_f32 v16, v20, v21
	s_nop 3
	ds_read_b128 v[4:7], v174 offset:4800
	v_mfma_f32_16x16x32_bf16 v[0:3], v[72:75], v[8:11], v[0:3]
	v_mul_f32_e32 v8, v14, v15
	v_cvt_pk_bf16_f32 v17, v22, v8
	v_lshlrev_b32_e32 v8, 16, v143
	s_waitcnt lgkmcnt(0)
	v_mfma_f32_16x16x32_bf16 v[0:3], v[68:71], v[4:7], v[0:3]
	v_lshlrev_b32_e32 v4, 16, v142
	global_store_dwordx2 v[12:13], v[16:17], off offset:2048
	s_waitcnt vmcnt(12)
	v_lshlrev_b32_e32 v10, 16, v140
	v_and_b32_e32 v12, 0xffff0000, v140
	v_and_b32_e32 v16, 0xffff0000, v141
	s_nop 1
	v_fma_f32 v5, v64, v4, v0
	v_and_b32_e32 v4, 0xffff0000, v142
	v_mul_f32_e32 v0, 0x3d372713, v5
	v_fma_f32 v1, v65, v4, v1
	v_mul_f32_e32 v0, v5, v0
	v_mul_f32_e32 v4, 0x3d372713, v1
	v_fma_f32 v9, v66, v8, v2
	v_fma_f32 v0, v5, v0, v5
	v_mul_f32_e32 v4, v1, v4
	v_mul_f32_e32 v2, 0x3d372713, v9
	v_mul_f32_e32 v0, 0x3fcc422a, v0
	v_fma_f32 v4, v1, v4, v1
	v_mul_f32_e32 v2, v9, v2
	v_mul_f32_e32 v0, 0xbfb8aa3b, v0
	v_mul_f32_e32 v4, 0x3fcc422a, v4
	v_fma_f32 v2, v9, v2, v9
	v_exp_f32_e32 v0, v0
	v_mul_f32_e32 v4, 0xbfb8aa3b, v4
	v_mul_f32_e32 v2, 0x3fcc422a, v2
	v_exp_f32_e32 v4, v4
	v_mul_f32_e32 v2, 0xbfb8aa3b, v2
	v_exp_f32_e32 v2, v2
	v_add_f32_e32 v0, 1.0, v0
	v_rcp_f32_e32 v11, v0
	v_add_f32_e32 v0, 1.0, v4
	v_rcp_f32_e32 v13, v0
	v_add_f32_e32 v0, 1.0, v2
	v_rcp_f32_e32 v15, v0
	v_and_b32_e32 v0, 0xffff0000, v143
	v_fmac_f32_e32 v3, v67, v0
	v_mul_f32_e32 v0, 0x3d372713, v3
	v_mul_f32_e32 v0, v3, v0
	v_fma_f32 v0, v3, v0, v3
	v_mul_f32_e32 v0, 0x3fcc422a, v0
	v_mul_f32_e32 v0, 0xbfb8aa3b, v0
	v_mul_f32_e32 v2, 0xbfb8aa3b, v10
	v_exp_f32_e32 v0, v0
	v_exp_f32_e32 v2, v2
	v_mul_f32_e32 v4, 0xbfb8aa3b, v12
	v_exp_f32_e32 v8, v4
	v_add_f32_e32 v14, 1.0, v0
	v_add_f32_e32 v0, 1.0, v2
	v_rcp_f32_e32 v4, v0
	v_rcp_f32_e32 v17, v14
	v_lshlrev_b32_e32 v14, 16, v141
	v_mul_f32_e32 v2, 0xbfb8aa3b, v14
	v_pk_mul_f32 v[4:5], v[4:5], v[10:11]
	v_exp_f32_e32 v2, v2
	v_mul_f32_e32 v10, v4, v5
	v_mul_f32_e32 v4, 0xbfb8aa3b, v16
	v_exp_f32_e32 v11, v4
	v_add_f32_e32 v0, 1.0, v8
	v_rcp_f32_e32 v0, v0
	v_add_f32_e32 v2, 1.0, v2
	v_rcp_f32_e32 v8, v2
	v_add_f32_e32 v2, 1.0, v11
	v_lshl_add_u64 v[6:7], s[86:87], 0, v[148:149]
	v_rcp_f32_e32 v2, v2
	v_lshl_add_u64 v[6:7], v[6:7], 0, s[94:95]
	v_pk_mul_f32 v[0:1], v[0:1], v[12:13]
	v_lshl_add_u64 v[6:7], v[6:7], 0, v[120:121]
	v_cvt_pk_bf16_f32 v4, v5, v1
	v_mul_f32_e32 v11, v0, v1
	v_pk_mul_f32 v[0:1], v[8:9], v[14:15]
	v_pk_mul_f32 v[2:3], v[2:3], v[16:17]
	v_mul_f32_e32 v8, v0, v1
	v_add_co_u32_e32 v0, vcc, 0x2000, v6
	v_cvt_pk_bf16_f32 v5, v1, v3
	v_add_u32_e32 v142, 0x400, v163
	s_nop 0
	v_addc_co_u32_e32 v1, vcc, 0, v7, vcc
	global_store_dwordx2 v[0:1], v[4:5], off
	v_mul_f32_e32 v1, v2, v3
	s_and_b64 vcc, exec, s[0:1]
	v_add_u32_e32 v141, 0x600, v163
	v_add_u32_e32 v140, 0x800, v163
	v_cvt_pk_bf16_f32 v0, v10, v11
	v_cvt_pk_bf16_f32 v1, v8, v1
	global_store_dwordx2 v[6:7], v[0:1], off offset:2048
	s_cbranch_vccnz .LBB0_787
	s_waitcnt vmcnt(6)
	ds_bpermute_b32 v202, v206, v104
	ds_bpermute_b32 v203, v206, v105
	ds_bpermute_b32 v204, v206, v106
	ds_bpermute_b32 v205, v206, v107
	ds_bpermute_b32 v210, v207, v104
	ds_bpermute_b32 v211, v207, v105
	ds_bpermute_b32 v212, v207, v106
	ds_bpermute_b32 v213, v207, v107
	v_mfma_f32_32x32x16_bf16 v[48:63], v[104:107], v[84:87], 0
	v_mfma_f32_32x32x16_bf16 v[32:47], v[104:107], v[88:91], 0
	v_mfma_f32_32x32x16_bf16 v[16:31], v[104:107], v[92:95], 0
	v_mfma_f32_32x32x16_bf16 v[0:15], v[104:107], v[96:99], 0
	s_waitcnt lgkmcnt(0)
	v_cmp_ne_u32_e64 s[26:27], 0, v208
	v_cndmask_b32_e64 v138, v202, v204, s[26:27]
	v_cndmask_b32_e64 v139, v203, v205, s[26:27]
	v_cndmask_b32_e64 v134, v210, v212, s[26:27]
	v_cndmask_b32_e64 v135, v211, v213, s[26:27]
	s_nop 8
	v_mov_b32_e32 v104, v48
	v_mov_b32_e32 v105, v32
	v_mov_b32_e32 v106, v16
	v_fma_f32 v104, v124, v108, v104
	v_fma_f32 v105, v125, v109, v105
	v_mov_b32_e32 v32, v49
	v_pk_fma_f32 v[104:105], v[130:131], v[110:111], v[104:105] neg_lo:[1,0,0] neg_hi:[1,0,0]
	v_mov_b32_e32 v48, v18
	v_mov_b32_e32 v107, v0
	v_pk_fma_f32 v[106:107], v[124:125], v[110:111], v[106:107]
	v_pk_fma_f32 v[32:33], v[124:125], v[104:105], v[32:33]
	v_pk_fma_f32 v[106:107], v[130:131], v[108:109], v[106:107]
	v_mov_b32_e32 v49, v2
	v_cvt_pk_bf16_f32 v0, v104, v106
	v_cvt_pk_bf16_f32 v16, v105, v107
	ds_write2_b32 v163, v0, v16 offset1:32
	v_mov_b32_e32 v0, v17
	v_pk_fma_f32 v[0:1], v[124:125], v[106:107], v[0:1]
	v_pk_fma_f32 v[32:33], v[130:131], v[106:107], v[32:33] neg_lo:[1,0,0] neg_hi:[1,0,0]
	v_pk_fma_f32 v[0:1], v[130:131], v[104:105], v[0:1]
	s_nop 0
	v_cvt_pk_bf16_f32 v16, v32, v0
	v_cvt_pk_bf16_f32 v17, v33, v1
	ds_write2_b32 v163, v16, v17 offset0:72 offset1:104
	v_mov_b32_e32 v16, v50
	v_mov_b32_e32 v17, v34
	v_pk_fma_f32 v[16:17], v[124:125], v[32:33], v[16:17]
	v_mov_b32_e32 v34, v51
	v_pk_fma_f32 v[16:17], v[130:131], v[0:1], v[16:17] neg_lo:[1,0,0] neg_hi:[1,0,0]
	v_pk_fma_f32 v[0:1], v[124:125], v[0:1], v[48:49]
	s_nop 0
	v_pk_fma_f32 v[0:1], v[130:131], v[32:33], v[0:1]
	v_pk_fma_f32 v[32:33], v[124:125], v[16:17], v[34:35]
	v_cvt_pk_bf16_f32 v2, v16, v0
	v_cvt_pk_bf16_f32 v18, v17, v1
	ds_write2_b32 v163, v2, v18 offset0:144 offset1:176
	v_mov_b32_e32 v2, v19
	v_pk_fma_f32 v[32:33], v[130:131], v[0:1], v[32:33] neg_lo:[1,0,0] neg_hi:[1,0,0]
	v_pk_fma_f32 v[0:1], v[124:125], v[0:1], v[2:3]
	v_and_b32_e32 v18, 0xffff0000, v137
	v_pk_fma_f32 v[0:1], v[130:131], v[16:17], v[0:1]
	v_mov_b32_e32 v16, v20
	v_cvt_pk_bf16_f32 v2, v32, v0
	v_cvt_pk_bf16_f32 v3, v33, v1
	ds_write2_b32 v163, v2, v3 offset0:216 offset1:248
	v_mov_b32_e32 v2, v52
	v_mov_b32_e32 v3, v36
	v_pk_fma_f32 v[2:3], v[124:125], v[32:33], v[2:3]
	v_mov_b32_e32 v17, v4
	v_pk_fma_f32 v[2:3], v[130:131], v[0:1], v[2:3] neg_lo:[1,0,0] neg_hi:[1,0,0]
	v_pk_fma_f32 v[0:1], v[124:125], v[0:1], v[16:17]
	v_mov_b32_e32 v36, v53
	v_pk_fma_f32 v[0:1], v[130:131], v[32:33], v[0:1]
	s_nop 0
	v_cvt_pk_bf16_f32 v4, v2, v0
	v_cvt_pk_bf16_f32 v16, v3, v1
	ds_write2_b32 v142, v4, v16 offset0:32 offset1:64
	v_mov_b32_e32 v4, v21
	v_pk_fma_f32 v[16:17], v[124:125], v[2:3], v[36:37]
	v_pk_fma_f32 v[4:5], v[124:125], v[0:1], v[4:5]
	v_pk_fma_f32 v[0:1], v[130:131], v[0:1], v[16:17] neg_lo:[1,0,0] neg_hi:[1,0,0]
	v_pk_fma_f32 v[2:3], v[130:131], v[2:3], v[4:5]
	v_mov_b32_e32 v16, v22
	v_cvt_pk_bf16_f32 v4, v0, v2
	v_cvt_pk_bf16_f32 v5, v1, v3
	ds_write2_b32 v142, v4, v5 offset0:104 offset1:136
	v_mov_b32_e32 v4, v54
	v_mov_b32_e32 v5, v38
	v_pk_fma_f32 v[4:5], v[124:125], v[0:1], v[4:5]
	v_mov_b32_e32 v17, v6
	v_pk_fma_f32 v[4:5], v[130:131], v[2:3], v[4:5] neg_lo:[1,0,0] neg_hi:[1,0,0]
	v_pk_fma_f32 v[2:3], v[124:125], v[2:3], v[16:17]
	v_mov_b32_e32 v38, v55
	v_pk_fma_f32 v[0:1], v[130:131], v[0:1], v[2:3]
	v_mov_b32_e32 v6, v23
	v_cvt_pk_bf16_f32 v2, v4, v0
	v_cvt_pk_bf16_f32 v3, v5, v1
	ds_write2_b32 v142, v2, v3 offset0:176 offset1:208
	v_pk_fma_f32 v[2:3], v[124:125], v[4:5], v[38:39]
	v_lshlrev_b32_e32 v16, 16, v137
	v_pk_fma_f32 v[2:3], v[130:131], v[0:1], v[2:3] neg_lo:[1,0,0] neg_hi:[1,0,0]
	v_pk_fma_f32 v[0:1], v[124:125], v[0:1], v[6:7]
	v_mov_b32_e32 v6, v24
	v_pk_fma_f32 v[0:1], v[130:131], v[4:5], v[0:1]
	v_mov_b32_e32 v7, v8
	v_cvt_pk_bf16_f32 v4, v2, v0
	v_cvt_pk_bf16_f32 v5, v3, v1
	ds_write2_b32 v141, v4, v5 offset0:120 offset1:152
	v_mov_b32_e32 v4, v56
	v_mov_b32_e32 v5, v40
	v_pk_fma_f32 v[4:5], v[124:125], v[2:3], v[4:5]
	v_mov_b32_e32 v40, v57
	v_pk_fma_f32 v[4:5], v[130:131], v[0:1], v[4:5] neg_lo:[1,0,0] neg_hi:[1,0,0]
	v_pk_fma_f32 v[0:1], v[124:125], v[0:1], v[6:7]
	v_mov_b32_e32 v8, v25
	v_pk_fma_f32 v[0:1], v[130:131], v[2:3], v[0:1]
	v_mov_b32_e32 v6, v26
	v_cvt_pk_bf16_f32 v2, v4, v0
	v_cvt_pk_bf16_f32 v3, v5, v1
	ds_write2_b32 v140, v2, v3 offset0:64 offset1:96
	v_pk_fma_f32 v[2:3], v[124:125], v[4:5], v[40:41]
	v_mov_b32_e32 v7, v10
	v_pk_fma_f32 v[2:3], v[130:131], v[0:1], v[2:3] neg_lo:[1,0,0] neg_hi:[1,0,0]
	v_pk_fma_f32 v[0:1], v[124:125], v[0:1], v[8:9]
	v_mov_b32_e32 v10, v27
	v_pk_fma_f32 v[0:1], v[130:131], v[4:5], v[0:1]
	v_lshlrev_b32_e32 v8, 16, v138
	v_cvt_pk_bf16_f32 v4, v2, v0
	v_cvt_pk_bf16_f32 v5, v3, v1
	ds_write2_b32 v140, v4, v5 offset0:136 offset1:168
	v_mov_b32_e32 v4, v58
	v_mov_b32_e32 v5, v42
	v_pk_fma_f32 v[4:5], v[124:125], v[2:3], v[4:5]
	v_mov_b32_e32 v42, v59
	v_pk_fma_f32 v[4:5], v[130:131], v[0:1], v[4:5] neg_lo:[1,0,0] neg_hi:[1,0,0]
	v_pk_fma_f32 v[0:1], v[124:125], v[0:1], v[6:7]
	v_mov_b32_e32 v6, v28
	v_pk_fma_f32 v[0:1], v[130:131], v[2:3], v[0:1]
	v_mov_b32_e32 v7, v12
	v_cvt_pk_bf16_f32 v2, v4, v0
	v_cvt_pk_bf16_f32 v3, v5, v1
	ds_write2_b32 v140, v2, v3 offset0:208 offset1:240
	v_pk_fma_f32 v[2:3], v[124:125], v[4:5], v[42:43]
	v_mov_b32_e32 v12, v29
	v_pk_fma_f32 v[2:3], v[130:131], v[0:1], v[2:3] neg_lo:[1,0,0] neg_hi:[1,0,0]
	v_pk_fma_f32 v[0:1], v[124:125], v[0:1], v[10:11]
	v_lshlrev_b32_e32 v10, 16, v136
	v_pk_fma_f32 v[0:1], v[130:131], v[4:5], v[0:1]
	s_nop 0
	v_cvt_pk_bf16_f32 v4, v2, v0
	v_cvt_pk_bf16_f32 v5, v3, v1
	ds_write2_b32 v115, v4, v5 offset0:24 offset1:56
	v_mov_b32_e32 v4, v60
	v_mov_b32_e32 v5, v44
	v_pk_fma_f32 v[4:5], v[124:125], v[2:3], v[4:5]
	v_mov_b32_e32 v44, v61
	v_pk_fma_f32 v[4:5], v[130:131], v[0:1], v[4:5] neg_lo:[1,0,0] neg_hi:[1,0,0]
	v_pk_fma_f32 v[0:1], v[124:125], v[0:1], v[6:7]
	v_mov_b32_e32 v6, v30
	v_pk_fma_f32 v[0:1], v[130:131], v[2:3], v[0:1]
	v_mov_b32_e32 v7, v14
	v_cvt_pk_bf16_f32 v2, v4, v0
	v_cvt_pk_bf16_f32 v3, v5, v1
	ds_write2_b32 v115, v2, v3 offset0:96 offset1:128
	v_pk_fma_f32 v[2:3], v[124:125], v[4:5], v[44:45]
	v_mov_b32_e32 v14, v31
	v_pk_fma_f32 v[2:3], v[130:131], v[0:1], v[2:3] neg_lo:[1,0,0] neg_hi:[1,0,0]
	v_pk_fma_f32 v[0:1], v[124:125], v[0:1], v[12:13]
	v_and_b32_e32 v12, 0xffff0000, v136
	v_pk_fma_f32 v[0:1], v[130:131], v[4:5], v[0:1]
	s_nop 0
	v_cvt_pk_bf16_f32 v4, v2, v0
	v_cvt_pk_bf16_f32 v5, v3, v1
	ds_write2_b32 v115, v4, v5 offset0:168 offset1:200
	v_mov_b32_e32 v4, v62
	v_mov_b32_e32 v5, v46
	v_pk_fma_f32 v[4:5], v[124:125], v[2:3], v[4:5]
	v_mov_b32_e32 v46, v63
	v_pk_fma_f32 v[4:5], v[130:131], v[0:1], v[4:5] neg_lo:[1,0,0] neg_hi:[1,0,0]
	v_pk_fma_f32 v[0:1], v[124:125], v[0:1], v[6:7]
	s_nop 0
	v_pk_fma_f32 v[0:1], v[130:131], v[2:3], v[0:1]
	s_nop 0
	v_cvt_pk_bf16_f32 v2, v4, v0
	v_cvt_pk_bf16_f32 v3, v5, v1
	ds_write2_b32 v114, v2, v3 offset0:112 offset1:144
	v_pk_fma_f32 v[2:3], v[124:125], v[4:5], v[46:47]
	s_nop 0
	v_pk_fma_f32 v[108:109], v[130:131], v[0:1], v[2:3] neg_lo:[1,0,0] neg_hi:[1,0,0]
	v_pk_fma_f32 v[0:1], v[124:125], v[0:1], v[14:15]
	s_nop 0
	v_pk_fma_f32 v[110:111], v[130:131], v[4:5], v[0:1]
	s_nop 0
	v_cvt_pk_bf16_f32 v0, v108, v110
	v_cvt_pk_bf16_f32 v1, v109, v111
	ds_write2_b32 v113, v0, v1 offset0:56 offset1:88
	ds_read_b128 v[0:3], v112
	ds_read_b128 v[4:7], v112 offset:64
	s_waitcnt lgkmcnt(1)
	v_mfma_f32_16x16x32_bf16 v[0:3], v[80:83], v[0:3], 0
	s_waitcnt lgkmcnt(0)
	v_mfma_f32_16x16x32_bf16 v[0:3], v[76:79], v[4:7], v[0:3]
	ds_read_b128 v[4:7], v112 offset:128
	s_waitcnt lgkmcnt(0)
	v_mfma_f32_16x16x32_bf16 v[0:3], v[72:75], v[4:7], v[0:3]
	ds_read_b128 v[4:7], v112 offset:192
	s_waitcnt lgkmcnt(0)
	v_mfma_f32_16x16x32_bf16 v[2:5], v[68:71], v[4:7], v[0:3]
	s_nop 4
	v_mov_b64_e32 v[0:1], s[86:87]
	v_mad_i64_i32 v[6:7], s[22:23], v165, s66, v[0:1]
	s_nop 0
	v_fma_f32 v9, v64, v8, v2
	v_mul_f32_e32 v2, 0x3d372713, v9
	v_mul_f32_e32 v2, v9, v2
	v_fma_f32 v2, v9, v2, v9
	v_mul_f32_e32 v2, 0x3fcc422a, v2
	v_mul_f32_e32 v2, 0xbfb8aa3b, v2
	v_exp_f32_e32 v2, v2
	v_lshl_add_u64 v[6:7], v[6:7], 0, s[94:95]
	v_lshl_add_u64 v[6:7], v[6:7], 0, v[120:121]
	v_mad_i64_i32 v[0:1], s[22:23], v164, s66, v[0:1]
	v_add_f32_e32 v2, 1.0, v2
	v_rcp_f32_e32 v11, v2
	v_and_b32_e32 v2, 0xffff0000, v138
	v_fma_f32 v3, v65, v2, v3
	v_mul_f32_e32 v2, 0x3d372713, v3
	v_mul_f32_e32 v2, v3, v2
	v_fma_f32 v2, v3, v2, v3
	v_mul_f32_e32 v2, 0x3fcc422a, v2
	v_mul_f32_e32 v2, 0xbfb8aa3b, v2
	v_exp_f32_e32 v2, v2
	v_lshl_add_u64 v[0:1], v[0:1], 0, s[94:95]
	v_lshl_add_u64 v[0:1], v[0:1], 0, v[120:121]
	v_add_f32_e32 v2, 1.0, v2
	v_rcp_f32_e32 v13, v2
	v_lshlrev_b32_e32 v2, 16, v139
	v_fma_f32 v15, v66, v2, v4
	v_mul_f32_e32 v2, 0x3d372713, v15
	v_mul_f32_e32 v2, v15, v2
	v_fma_f32 v2, v15, v2, v15
	v_mul_f32_e32 v2, 0x3fcc422a, v2
	v_mul_f32_e32 v2, 0xbfb8aa3b, v2
	v_exp_f32_e32 v2, v2
	s_nop 0
	v_add_f32_e32 v2, 1.0, v2
	v_rcp_f32_e32 v17, v2
	v_and_b32_e32 v2, 0xffff0000, v139
	v_fmac_f32_e32 v5, v67, v2
	v_mul_f32_e32 v2, 0x3d372713, v5
	v_mul_f32_e32 v2, v5, v2
	v_fma_f32 v2, v5, v2, v5
	v_mul_f32_e32 v2, 0x3fcc422a, v2
	v_mul_f32_e32 v2, 0xbfb8aa3b, v2
	v_exp_f32_e32 v2, v2
	s_nop 0
	v_add_f32_e32 v2, 1.0, v2
	v_rcp_f32_e32 v19, v2
	v_mul_f32_e32 v2, 0xbfb8aa3b, v10
	v_exp_f32_e32 v2, v2
	s_nop 0
	v_add_f32_e32 v2, 1.0, v2
	v_rcp_f32_e32 v8, v2
	v_mul_f32_e32 v2, 0xbfb8aa3b, v12
	v_exp_f32_e32 v2, v2
	v_pk_mul_f32 v[8:9], v[8:9], v[10:11]
	s_nop 0
	v_mul_f32_e32 v10, v8, v9
	v_add_f32_e32 v2, 1.0, v2
	v_rcp_f32_e32 v2, v2
	s_nop 0
	v_pk_mul_f32 v[2:3], v[2:3], v[12:13]
	s_nop 0
	v_mul_f32_e32 v11, v2, v3
	v_mul_f32_e32 v2, 0xbfb8aa3b, v16
	v_exp_f32_e32 v2, v2
	v_cvt_pk_bf16_f32 v8, v9, v3
	s_nop 0
	v_add_f32_e32 v2, 1.0, v2
	v_rcp_f32_e32 v14, v2
	s_nop 0
	v_pk_mul_f32 v[2:3], v[14:15], v[16:17]
	s_nop 0
	v_mul_f32_e32 v12, v2, v3
	v_mul_f32_e32 v2, 0xbfb8aa3b, v18
	v_exp_f32_e32 v2, v2
	v_lshlrev_b32_e32 v14, 16, v133
	v_and_b32_e32 v16, 0xffff0000, v133
	v_add_f32_e32 v2, 1.0, v2
	v_rcp_f32_e32 v4, v2
	v_add_co_u32_e32 v2, vcc, s92, v6
	v_pk_mul_f32 v[4:5], v[4:5], v[18:19]
	s_nop 0
	v_cvt_pk_bf16_f32 v9, v3, v5
	v_addc_co_u32_e32 v3, vcc, 0, v7, vcc
	global_store_dwordx2 v[2:3], v[8:9], off
	v_mul_f32_e32 v3, v4, v5
	v_cvt_pk_bf16_f32 v2, v10, v11
	v_cvt_pk_bf16_f32 v3, v12, v3
	global_store_dwordx2 v[6:7], v[2:3], off offset:2048
	ds_read_b128 v[2:5], v112 offset:4608
	ds_read_b128 v[6:9], v112 offset:4672
	s_waitcnt lgkmcnt(1)
	v_mfma_f32_16x16x32_bf16 v[2:5], v[80:83], v[2:5], 0
	v_and_b32_e32 v10, 0xffff0000, v132
	s_waitcnt lgkmcnt(0)
	v_mfma_f32_16x16x32_bf16 v[2:5], v[76:79], v[6:9], v[2:5]
	ds_read_b128 v[6:9], v112 offset:4736
	s_waitcnt lgkmcnt(0)
	v_mfma_f32_16x16x32_bf16 v[2:5], v[72:75], v[6:9], v[2:5]
	ds_read_b128 v[6:9], v112 offset:4800
	s_waitcnt lgkmcnt(0)
	v_mfma_f32_16x16x32_bf16 v[2:5], v[68:71], v[6:9], v[2:5]
	v_lshlrev_b32_e32 v6, 16, v134
	v_lshlrev_b32_e32 v8, 16, v132
	s_nop 5
	v_fma_f32 v7, v64, v6, v2
	v_mul_f32_e32 v2, 0x3d372713, v7
	v_mul_f32_e32 v2, v7, v2
	v_fma_f32 v2, v7, v2, v7
	v_mul_f32_e32 v2, 0x3fcc422a, v2
	v_mul_f32_e32 v2, 0xbfb8aa3b, v2
	v_exp_f32_e32 v2, v2
	s_nop 0
	v_add_f32_e32 v2, 1.0, v2
	v_rcp_f32_e32 v9, v2
	v_and_b32_e32 v2, 0xffff0000, v134
	v_fma_f32 v3, v65, v2, v3
	v_mul_f32_e32 v2, 0x3d372713, v3
	v_mul_f32_e32 v2, v3, v2
	v_fma_f32 v2, v3, v2, v3
	v_mul_f32_e32 v2, 0x3fcc422a, v2
	v_mul_f32_e32 v2, 0xbfb8aa3b, v2
	v_exp_f32_e32 v2, v2
	s_nop 0
	v_add_f32_e32 v2, 1.0, v2
	v_rcp_f32_e32 v11, v2
	v_lshlrev_b32_e32 v2, 16, v135
	v_fma_f32 v13, v66, v2, v4
	v_mul_f32_e32 v2, 0x3d372713, v13
	v_mul_f32_e32 v2, v13, v2
	v_fma_f32 v2, v13, v2, v13
	v_mul_f32_e32 v2, 0x3fcc422a, v2
	v_mul_f32_e32 v2, 0xbfb8aa3b, v2
	v_exp_f32_e32 v2, v2
	s_nop 0
	v_add_f32_e32 v2, 1.0, v2
	v_rcp_f32_e32 v15, v2
	v_and_b32_e32 v2, 0xffff0000, v135
	v_fmac_f32_e32 v5, v67, v2
	v_mul_f32_e32 v2, 0x3d372713, v5
	v_mul_f32_e32 v2, v5, v2
	v_fma_f32 v2, v5, v2, v5
	v_mul_f32_e32 v2, 0x3fcc422a, v2
	v_mul_f32_e32 v2, 0xbfb8aa3b, v2
	v_exp_f32_e32 v2, v2
	s_nop 0
	v_add_f32_e32 v2, 1.0, v2
	v_rcp_f32_e32 v17, v2
	v_mul_f32_e32 v2, 0xbfb8aa3b, v8
	v_exp_f32_e32 v2, v2
	s_nop 0
	v_add_f32_e32 v2, 1.0, v2
	v_rcp_f32_e32 v6, v2
	v_mul_f32_e32 v2, 0xbfb8aa3b, v10
	v_exp_f32_e32 v2, v2
	v_pk_mul_f32 v[6:7], v[6:7], v[8:9]
	s_nop 0
	v_mul_f32_e32 v8, v6, v7
	v_add_f32_e32 v2, 1.0, v2
	v_rcp_f32_e32 v2, v2
	s_nop 0
	v_pk_mul_f32 v[2:3], v[2:3], v[10:11]
	s_nop 0
	v_mul_f32_e32 v9, v2, v3
	v_mul_f32_e32 v2, 0xbfb8aa3b, v14
	v_exp_f32_e32 v2, v2
	v_cvt_pk_bf16_f32 v6, v7, v3
	s_nop 0
	v_add_f32_e32 v2, 1.0, v2
	v_rcp_f32_e32 v12, v2
	s_nop 0
	v_pk_mul_f32 v[2:3], v[12:13], v[14:15]
	s_nop 0
	v_mul_f32_e32 v10, v2, v3
	v_mul_f32_e32 v2, 0xbfb8aa3b, v16
	v_exp_f32_e32 v2, v2
	s_nop 0
	v_add_f32_e32 v2, 1.0, v2
	v_rcp_f32_e32 v4, v2
	v_add_co_u32_e32 v2, vcc, 0x2000, v0
	v_pk_mul_f32 v[4:5], v[4:5], v[16:17]
	s_nop 0
	v_cvt_pk_bf16_f32 v7, v3, v5
	v_addc_co_u32_e32 v3, vcc, 0, v1, vcc
	global_store_dwordx2 v[2:3], v[6:7], off
	v_mul_f32_e32 v3, v4, v5
	v_cvt_pk_bf16_f32 v2, v8, v9
	v_cvt_pk_bf16_f32 v3, v10, v3
	global_store_dwordx2 v[0:1], v[2:3], off offset:2048
	s_and_b64 vcc, exec, s[0:1]
	s_cbranch_vccz .LBB0_788
